# hand-written P1 kind-0 epilogue body (plain / gelu / gate-byte modes as straight-line packed code, q-scale folded into rstd), old per-block mode-dispatch code removed
# speedup vs baseline: 1.0167x; 1.0015x over previous
; __device__ __forceinline__ float row_rstd(const float* ssp, int row, int fq) {
;     const f32x4 a = *(const f32x4*)(ssp + (size_t)row * 32 + 8 * fq), b = *(const f32x4*)(ssp + (size_t)row * 32 + 8 * fq + 4);
;     float s = ((a[0] + a[1]) + (a[2] + a[3])) + ((b[0] + b[1]) + (b[2] + b[3]));
;     s += __shfl_xor(s, 16); s += __shfl_xor(s, 32);
;     return __builtin_amdgcn_rsqf(s * (1.0f / 2048.0f) + 1e-6f);
; }
;     __device__ __forceinline__ void operator()(f32x4 (&acc)[2][2][4][2], const Unit& u, int wr, int wc, int fr, int fq) const {
;     ...
;                     float rstd = row_rstd(ss, row, fq); if (mode == 1) rstd *= 0.125f;
.LBB0_196:
	v_lshl_add_u32 v2, s82, 8, v211
	v_lshlrev_b32_e32 v2, 7, v2
	v_mov_b32_e32 v3, 0
	v_lshl_add_u64 v[144:145], v[178:179], 0, v[2:3]
	v_add_u32_e32 v2, 0x1000, v2
	v_lshl_add_u64 v[208:209], v[178:179], 0, v[2:3]
	v_add_u32_e32 v2, 0x3000, v2
	v_lshl_add_u64 v[230:231], v[178:179], 0, v[2:3]
	v_add_u32_e32 v2, 0x1000, v2
	v_lshl_add_u64 v[238:239], v[178:179], 0, v[2:3]
	global_load_dwordx4 v[132:135], v[144:145], off
	global_load_dwordx4 v[136:139], v[144:145], off offset:16
	global_load_dwordx4 v[140:143], v[144:145], off offset:2048
	global_load_dwordx4 v[148:151], v[144:145], off offset:2064
	global_load_dwordx4 v[152:155], v[208:209], off
	global_load_dwordx4 v[184:187], v[208:209], off offset:16
	global_load_dwordx4 v[188:191], v[208:209], off offset:2048
	global_load_dwordx4 v[192:195], v[208:209], off offset:2064
	global_load_dwordx4 v[196:199], v[230:231], off
	global_load_dwordx4 v[200:203], v[230:231], off offset:16
	global_load_dwordx4 v[204:207], v[230:231], off offset:2048
	global_load_dwordx4 v[218:221], v[230:231], off offset:2064
	global_load_dwordx4 v[222:225], v[238:239], off
	global_load_dwordx4 v[226:229], v[238:239], off offset:16
	global_load_dwordx4 v[246:249], v[238:239], off offset:2048
	global_load_dwordx4 v[250:253], v[238:239], off offset:2064
	v_xor_b32_e32 v0, 16, v241
	v_xor_b32_e32 v162, 32, v241
	v_lshlrev_b32_e32 v0, 2, v0
	v_lshlrev_b32_e32 v162, 2, v162
	s_waitcnt vmcnt(14)
	v_add_f32_e32 v132, v132, v133
	v_add_f32_e32 v134, v134, v135
	v_add_f32_e32 v136, v136, v137
	v_add_f32_e32 v138, v138, v139
	v_add_f32_e32 v132, v132, v134
	v_add_f32_e32 v136, v136, v138
	v_add_f32_e32 v132, v132, v136
	s_waitcnt vmcnt(12)
	v_add_f32_e32 v140, v140, v141
	v_add_f32_e32 v142, v142, v143
	v_add_f32_e32 v148, v148, v149
	v_add_f32_e32 v150, v150, v151
	v_add_f32_e32 v140, v140, v142
	v_add_f32_e32 v148, v148, v150
	v_add_f32_e32 v140, v140, v148
	s_waitcnt vmcnt(10)
	v_add_f32_e32 v152, v152, v153
	v_add_f32_e32 v154, v154, v155
	v_add_f32_e32 v184, v184, v185
	v_add_f32_e32 v186, v186, v187
	v_add_f32_e32 v152, v152, v154
	v_add_f32_e32 v184, v184, v186
	v_add_f32_e32 v152, v152, v184
	s_waitcnt vmcnt(8)
	v_add_f32_e32 v188, v188, v189
	v_add_f32_e32 v190, v190, v191
	v_add_f32_e32 v192, v192, v193
	v_add_f32_e32 v194, v194, v195
	v_add_f32_e32 v188, v188, v190
	v_add_f32_e32 v192, v192, v194
	v_add_f32_e32 v188, v188, v192
	s_waitcnt vmcnt(6)
	v_add_f32_e32 v196, v196, v197
	v_add_f32_e32 v198, v198, v199
	v_add_f32_e32 v200, v200, v201
	v_add_f32_e32 v202, v202, v203
	v_add_f32_e32 v196, v196, v198
	v_add_f32_e32 v200, v200, v202
	v_add_f32_e32 v196, v196, v200
	s_waitcnt vmcnt(4)
	v_add_f32_e32 v204, v204, v205
	v_add_f32_e32 v206, v206, v207
	v_add_f32_e32 v218, v218, v219
	v_add_f32_e32 v220, v220, v221
	v_add_f32_e32 v204, v204, v206
	v_add_f32_e32 v218, v218, v220
	v_add_f32_e32 v204, v204, v218
	s_waitcnt vmcnt(2)
	v_add_f32_e32 v222, v222, v223
	v_add_f32_e32 v224, v224, v225
	v_add_f32_e32 v226, v226, v227
	v_add_f32_e32 v228, v228, v229
	v_add_f32_e32 v222, v222, v224
	v_add_f32_e32 v226, v226, v228
	v_add_f32_e32 v222, v222, v226
	s_waitcnt vmcnt(0)
	v_add_f32_e32 v246, v246, v247
	v_add_f32_e32 v248, v248, v249
	v_add_f32_e32 v250, v250, v251
	v_add_f32_e32 v252, v252, v253
	v_add_f32_e32 v246, v246, v248
	v_add_f32_e32 v250, v250, v252
	v_add_f32_e32 v246, v246, v250
	ds_bpermute_b32 v136, v0, v132
	ds_bpermute_b32 v148, v0, v140
	ds_bpermute_b32 v184, v0, v152
	ds_bpermute_b32 v192, v0, v188
	ds_bpermute_b32 v200, v0, v196
	ds_bpermute_b32 v218, v0, v204
	ds_bpermute_b32 v226, v0, v222
	ds_bpermute_b32 v250, v0, v246
	s_waitcnt lgkmcnt(0)
	v_add_f32_e32 v132, v132, v136
	v_add_f32_e32 v140, v140, v148
	v_add_f32_e32 v152, v152, v184
	v_add_f32_e32 v188, v188, v192
	v_add_f32_e32 v196, v196, v200
	v_add_f32_e32 v204, v204, v218
	v_add_f32_e32 v222, v222, v226
	v_add_f32_e32 v246, v246, v250
	ds_bpermute_b32 v136, v162, v132
	ds_bpermute_b32 v148, v162, v140
	ds_bpermute_b32 v184, v162, v152
	ds_bpermute_b32 v192, v162, v188
	ds_bpermute_b32 v200, v162, v196
	ds_bpermute_b32 v218, v162, v204
	ds_bpermute_b32 v226, v162, v222
	ds_bpermute_b32 v250, v162, v246
	s_waitcnt lgkmcnt(0)
	v_add_f32_e32 v132, v132, v136
	v_add_f32_e32 v140, v140, v148
	v_add_f32_e32 v152, v152, v184
	v_add_f32_e32 v188, v188, v192
	v_add_f32_e32 v196, v196, v200
	v_add_f32_e32 v204, v204, v218
	v_add_f32_e32 v222, v222, v226
	v_add_f32_e32 v246, v246, v250
	v_fmamk_f32 v132, v132, 0x3a000000, v243
	v_fmamk_f32 v140, v140, 0x3a000000, v243
	v_fmamk_f32 v152, v152, 0x3a000000, v243
	v_fmamk_f32 v188, v188, 0x3a000000, v243
	v_fmamk_f32 v196, v196, 0x3a000000, v243
	v_fmamk_f32 v204, v204, 0x3a000000, v243
	v_fmamk_f32 v222, v222, 0x3a000000, v243
	v_fmamk_f32 v246, v246, 0x3a000000, v243
	v_rsq_f32_e32 v132, v132
	v_rsq_f32_e32 v140, v140
	v_rsq_f32_e32 v152, v152
	v_rsq_f32_e32 v188, v188
	v_rsq_f32_e32 v196, v196
	v_rsq_f32_e32 v204, v204
	v_rsq_f32_e32 v222, v222
	v_rsq_f32_e32 v246, v246
	s_cmp_lg_u64 s[18:19], 0
	s_cselect_b32 s21, 0x3e000000, 1.0
	v_mul_f32_e32 v132, s21, v132
	v_mul_f32_e32 v140, s21, v140
	v_mul_f32_e32 v152, s21, v152
	v_mul_f32_e32 v188, s21, v188
	v_mul_f32_e32 v196, s21, v196
	v_mul_f32_e32 v204, s21, v204
	v_mul_f32_e32 v222, s21, v222
	v_mul_f32_e32 v246, s21, v246
	s_nop 0
	v_pk_mul_f32 v[128:129], v[128:129], v[132:133] op_sel_hi:[1,0]
	v_pk_mul_f32 v[130:131], v[130:131], v[132:133] op_sel_hi:[1,0]
	v_pk_mul_f32 v[124:125], v[124:125], v[132:133] op_sel_hi:[1,0]
	v_pk_mul_f32 v[126:127], v[126:127], v[132:133] op_sel_hi:[1,0]
	v_pk_mul_f32 v[120:121], v[120:121], v[132:133] op_sel_hi:[1,0]
; __device__ __forceinline__ f32x4 gelu4(f32x4 v) { return (f32x4){gelu_tanh(v[0]), gelu_tanh(v[1]), gelu_tanh(v[2]), gelu_tanh(v[3])}; }
; __device__ __forceinline__ f32x4 sigm4(f32x4 v) { return (f32x4){sigmoid_f(v[0]), sigmoid_f(v[1]), sigmoid_f(v[2]), sigmoid_f(v[3])}; }
; __device__ __forceinline__ u32x4 pack8(f32x4 a, f32x4 b) { u32x4 w; w.x = cvt_pk_bf16(a[0], a[1]); w.y = cvt_pk_bf16(a[2], a[3]); w.z = cvt_pk_bf16(b[0], b[1]); w.w = cvt_pk_bf16(b[2], b[3]); return w; }
;     __device__ __forceinline__ void operator()(f32x4 (&acc)[2][2][4][2], const Unit& u, int wr, int wc, int fr, int fq) const {
;     ...
;             const int row0 = u.pm * BM + wr * 64 + fr, col0 = colt + wc * 64 + 8 * fq;
; #pragma unroll
;             for (int ai = 0; ai < 2; ++ai)
; #pragma unroll
;                 for (int m = 0; m < 4; ++m) {
;                     const int row = row0 + ai * HALF + m * 16;
;                     float rstd = row_rstd(ss, row, fq); if (mode == 1) rstd *= 0.125f;
;                     bf16_t* rowp = base + (size_t)row * ldc + col0;
; #pragma unroll
;                     for (int bj = 0; bj < 2; ++bj) {
;                         f32x4 v0 = acc[ai][bj][m][0] * rstd, v1 = acc[ai][bj][m][1] * rstd;
;                         if (mode == 3) { u32x2 w; w.x = gate_q4(sigm4(v0)); w.y = gate_q4(sigm4(v1)); *(u32x2*)((unsigned char*)Gt + (size_t)row * 4096 + col0 + bj * 32) = w; continue; }
;                         if (mode == 0) { v0 = gelu4(v0); v1 = gelu4(v1); }
;                         *(u32x4*)(rowp + bj * 32) = pack8(v0, v1);
	v_pk_mul_f32 v[122:123], v[122:123], v[132:133] op_sel_hi:[1,0]
	v_pk_mul_f32 v[116:117], v[116:117], v[132:133] op_sel_hi:[1,0]
	v_pk_mul_f32 v[118:119], v[118:119], v[132:133] op_sel_hi:[1,0]
	v_pk_mul_f32 v[112:113], v[112:113], v[140:141] op_sel_hi:[1,0]
	v_pk_mul_f32 v[114:115], v[114:115], v[140:141] op_sel_hi:[1,0]
	v_pk_mul_f32 v[108:109], v[108:109], v[140:141] op_sel_hi:[1,0]
	v_pk_mul_f32 v[110:111], v[110:111], v[140:141] op_sel_hi:[1,0]
	v_pk_mul_f32 v[104:105], v[104:105], v[140:141] op_sel_hi:[1,0]
	v_pk_mul_f32 v[106:107], v[106:107], v[140:141] op_sel_hi:[1,0]
	v_pk_mul_f32 v[100:101], v[100:101], v[140:141] op_sel_hi:[1,0]
	v_pk_mul_f32 v[102:103], v[102:103], v[140:141] op_sel_hi:[1,0]
	v_pk_mul_f32 v[96:97], v[96:97], v[152:153] op_sel_hi:[1,0]
	v_pk_mul_f32 v[98:99], v[98:99], v[152:153] op_sel_hi:[1,0]
	v_pk_mul_f32 v[92:93], v[92:93], v[152:153] op_sel_hi:[1,0]
	v_pk_mul_f32 v[94:95], v[94:95], v[152:153] op_sel_hi:[1,0]
	v_pk_mul_f32 v[88:89], v[88:89], v[152:153] op_sel_hi:[1,0]
	v_pk_mul_f32 v[90:91], v[90:91], v[152:153] op_sel_hi:[1,0]
	v_pk_mul_f32 v[84:85], v[84:85], v[152:153] op_sel_hi:[1,0]
	v_pk_mul_f32 v[86:87], v[86:87], v[152:153] op_sel_hi:[1,0]
	v_pk_mul_f32 v[80:81], v[80:81], v[188:189] op_sel_hi:[1,0]
	v_pk_mul_f32 v[82:83], v[82:83], v[188:189] op_sel_hi:[1,0]
	v_pk_mul_f32 v[76:77], v[76:77], v[188:189] op_sel_hi:[1,0]
	v_pk_mul_f32 v[78:79], v[78:79], v[188:189] op_sel_hi:[1,0]
	v_pk_mul_f32 v[72:73], v[72:73], v[188:189] op_sel_hi:[1,0]
	v_pk_mul_f32 v[74:75], v[74:75], v[188:189] op_sel_hi:[1,0]
	v_pk_mul_f32 v[68:69], v[68:69], v[188:189] op_sel_hi:[1,0]
	v_pk_mul_f32 v[70:71], v[70:71], v[188:189] op_sel_hi:[1,0]
	v_pk_mul_f32 v[64:65], v[64:65], v[196:197] op_sel_hi:[1,0]
	v_pk_mul_f32 v[66:67], v[66:67], v[196:197] op_sel_hi:[1,0]
	v_pk_mul_f32 v[60:61], v[60:61], v[196:197] op_sel_hi:[1,0]
	v_pk_mul_f32 v[62:63], v[62:63], v[196:197] op_sel_hi:[1,0]
	v_pk_mul_f32 v[56:57], v[56:57], v[196:197] op_sel_hi:[1,0]
	v_pk_mul_f32 v[58:59], v[58:59], v[196:197] op_sel_hi:[1,0]
	v_pk_mul_f32 v[52:53], v[52:53], v[196:197] op_sel_hi:[1,0]
	v_pk_mul_f32 v[54:55], v[54:55], v[196:197] op_sel_hi:[1,0]
	v_pk_mul_f32 v[48:49], v[48:49], v[204:205] op_sel_hi:[1,0]
	v_pk_mul_f32 v[50:51], v[50:51], v[204:205] op_sel_hi:[1,0]
	v_pk_mul_f32 v[44:45], v[44:45], v[204:205] op_sel_hi:[1,0]
	v_pk_mul_f32 v[46:47], v[46:47], v[204:205] op_sel_hi:[1,0]
	v_pk_mul_f32 v[40:41], v[40:41], v[204:205] op_sel_hi:[1,0]
	v_pk_mul_f32 v[42:43], v[42:43], v[204:205] op_sel_hi:[1,0]
	v_pk_mul_f32 v[36:37], v[36:37], v[204:205] op_sel_hi:[1,0]
	v_pk_mul_f32 v[38:39], v[38:39], v[204:205] op_sel_hi:[1,0]
	v_pk_mul_f32 v[32:33], v[32:33], v[222:223] op_sel_hi:[1,0]
	v_pk_mul_f32 v[34:35], v[34:35], v[222:223] op_sel_hi:[1,0]
	v_pk_mul_f32 v[28:29], v[28:29], v[222:223] op_sel_hi:[1,0]
	v_pk_mul_f32 v[30:31], v[30:31], v[222:223] op_sel_hi:[1,0]
	v_pk_mul_f32 v[24:25], v[24:25], v[222:223] op_sel_hi:[1,0]
	v_pk_mul_f32 v[26:27], v[26:27], v[222:223] op_sel_hi:[1,0]
	v_pk_mul_f32 v[20:21], v[20:21], v[222:223] op_sel_hi:[1,0]
	v_pk_mul_f32 v[22:23], v[22:23], v[222:223] op_sel_hi:[1,0]
	v_pk_mul_f32 v[16:17], v[16:17], v[246:247] op_sel_hi:[1,0]
	v_pk_mul_f32 v[18:19], v[18:19], v[246:247] op_sel_hi:[1,0]
	v_pk_mul_f32 v[12:13], v[12:13], v[246:247] op_sel_hi:[1,0]
	v_pk_mul_f32 v[14:15], v[14:15], v[246:247] op_sel_hi:[1,0]
	v_pk_mul_f32 v[8:9], v[8:9], v[246:247] op_sel_hi:[1,0]
	v_pk_mul_f32 v[10:11], v[10:11], v[246:247] op_sel_hi:[1,0]
	v_pk_mul_f32 v[4:5], v[4:5], v[246:247] op_sel_hi:[1,0]
	v_pk_mul_f32 v[6:7], v[6:7], v[246:247] op_sel_hi:[1,0]
	v_lshl_add_u32 v184, s82, 8, v211
	v_add_u32_e32 v185, s20, v215
	s_mov_b32 s42, 1.0
	s_mov_b32 s43, 1.0
	s_and_b64 vcc, exec, s[12:13]
	s_cbranch_vccnz .Lp1e_gates
	v_lshlrev_b32_e32 v186, 11, v184
	v_lshl_add_u32 v186, v185, 1, v186
	s_and_b64 vcc, exec, s[16:17]
	s_cbranch_vccnz .Lp1e_gelu
	v_cvt_pk_bf16_f32 v206, v128, v129
	v_cvt_pk_bf16_f32 v207, v130, v131
	v_cvt_pk_bf16_f32 v208, v124, v125
	v_cvt_pk_bf16_f32 v209, v126, v127
	global_store_dwordx4 v186, v[206:209], s[34:35]
	v_cvt_pk_bf16_f32 v218, v120, v121
	v_cvt_pk_bf16_f32 v219, v122, v123
	v_cvt_pk_bf16_f32 v220, v116, v117
	v_cvt_pk_bf16_f32 v221, v118, v119
	global_store_dwordx4 v186, v[218:221], s[34:35] offset:64
	v_add_u32_e32 v187, 0x8000, v186
	v_cvt_pk_bf16_f32 v224, v112, v113
	v_cvt_pk_bf16_f32 v225, v114, v115
	v_cvt_pk_bf16_f32 v226, v108, v109
	v_cvt_pk_bf16_f32 v227, v110, v111
	global_store_dwordx4 v187, v[224:227], s[34:35]
	v_cvt_pk_bf16_f32 v228, v104, v105
	v_cvt_pk_bf16_f32 v229, v106, v107
	v_cvt_pk_bf16_f32 v230, v100, v101
	v_cvt_pk_bf16_f32 v231, v102, v103
	global_store_dwordx4 v187, v[228:231], s[34:35] offset:64
	v_add_u32_e32 v187, 0x10000, v186
	v_cvt_pk_bf16_f32 v206, v96, v97
	v_cvt_pk_bf16_f32 v207, v98, v99
	v_cvt_pk_bf16_f32 v208, v92, v93
	v_cvt_pk_bf16_f32 v209, v94, v95
	global_store_dwordx4 v187, v[206:209], s[34:35]
	v_cvt_pk_bf16_f32 v218, v88, v89
	v_cvt_pk_bf16_f32 v219, v90, v91
	v_cvt_pk_bf16_f32 v220, v84, v85
	v_cvt_pk_bf16_f32 v221, v86, v87
	global_store_dwordx4 v187, v[218:221], s[34:35] offset:64
	v_add_u32_e32 v187, 0x18000, v186
	v_cvt_pk_bf16_f32 v224, v80, v81
	v_cvt_pk_bf16_f32 v225, v82, v83
	v_cvt_pk_bf16_f32 v226, v76, v77
	v_cvt_pk_bf16_f32 v227, v78, v79
	global_store_dwordx4 v187, v[224:227], s[34:35]
	v_cvt_pk_bf16_f32 v228, v72, v73
	v_cvt_pk_bf16_f32 v229, v74, v75
	v_cvt_pk_bf16_f32 v230, v68, v69
	v_cvt_pk_bf16_f32 v231, v70, v71
	global_store_dwordx4 v187, v[228:231], s[34:35] offset:64
	v_add_u32_e32 v187, 0x40000, v186
	v_cvt_pk_bf16_f32 v206, v64, v65
; __device__ __forceinline__ float fast_rcp(float x) { return __builtin_amdgcn_rcpf(x); }
; __device__ __forceinline__ float fast_exp2(float x) { return __builtin_amdgcn_exp2f(x); }
; __device__ __forceinline__ f32x4 sigm4(f32x4 v) { return (f32x4){sigmoid_f(v[0]), sigmoid_f(v[1]), sigmoid_f(v[2]), sigmoid_f(v[3])}; }
; __device__ __forceinline__ u32x4 pack8(f32x4 a, f32x4 b) { u32x4 w; w.x = cvt_pk_bf16(a[0], a[1]); w.y = cvt_pk_bf16(a[2], a[3]); w.z = cvt_pk_bf16(b[0], b[1]); w.w = cvt_pk_bf16(b[2], b[3]); return w; }
; __device__ __forceinline__ float gelu_tanh(float x) { const float t = x + 0.044715f * x * x * x; return x * fast_rcp(1.0f + fast_exp2(-2.3022081981f * t)); }
; __device__ __forceinline__ f32x4 gelu4(f32x4 v) { return (f32x4){gelu_tanh(v[0]), gelu_tanh(v[1]), gelu_tanh(v[2]), gelu_tanh(v[3])}; }
;     __device__ __forceinline__ void operator()(f32x4 (&acc)[2][2][4][2], const Unit& u, int wr, int wc, int fr, int fq) const {
;     ...
;                         f32x4 v0 = acc[ai][bj][m][0] * rstd, v1 = acc[ai][bj][m][1] * rstd;
;                         if (mode == 3) { u32x2 w; w.x = gate_q4(sigm4(v0)); w.y = gate_q4(sigm4(v1)); *(u32x2*)((unsigned char*)Gt + (size_t)row * 4096 + col0 + bj * 32) = w; continue; }
;                         if (mode == 0) { v0 = gelu4(v0); v1 = gelu4(v1); }
;                         *(u32x4*)(rowp + bj * 32) = pack8(v0, v1);
	v_cvt_pk_bf16_f32 v207, v66, v67
	v_cvt_pk_bf16_f32 v208, v60, v61
	v_cvt_pk_bf16_f32 v209, v62, v63
	global_store_dwordx4 v187, v[206:209], s[34:35]
	v_cvt_pk_bf16_f32 v218, v56, v57
	v_cvt_pk_bf16_f32 v219, v58, v59
	v_cvt_pk_bf16_f32 v220, v52, v53
	v_cvt_pk_bf16_f32 v221, v54, v55
	global_store_dwordx4 v187, v[218:221], s[34:35] offset:64
	v_add_u32_e32 v187, 0x48000, v186
	v_cvt_pk_bf16_f32 v224, v48, v49
	v_cvt_pk_bf16_f32 v225, v50, v51
	v_cvt_pk_bf16_f32 v226, v44, v45
	v_cvt_pk_bf16_f32 v227, v46, v47
	global_store_dwordx4 v187, v[224:227], s[34:35]
	v_cvt_pk_bf16_f32 v228, v40, v41
	v_cvt_pk_bf16_f32 v229, v42, v43
	v_cvt_pk_bf16_f32 v230, v36, v37
	v_cvt_pk_bf16_f32 v231, v38, v39
	global_store_dwordx4 v187, v[228:231], s[34:35] offset:64
	v_add_u32_e32 v187, 0x50000, v186
	v_cvt_pk_bf16_f32 v206, v32, v33
	v_cvt_pk_bf16_f32 v207, v34, v35
	v_cvt_pk_bf16_f32 v208, v28, v29
	v_cvt_pk_bf16_f32 v209, v30, v31
	global_store_dwordx4 v187, v[206:209], s[34:35]
	v_cvt_pk_bf16_f32 v218, v24, v25
	v_cvt_pk_bf16_f32 v219, v26, v27
	v_cvt_pk_bf16_f32 v220, v20, v21
	v_cvt_pk_bf16_f32 v221, v22, v23
	global_store_dwordx4 v187, v[218:221], s[34:35] offset:64
	v_add_u32_e32 v187, 0x58000, v186
	v_cvt_pk_bf16_f32 v224, v16, v17
	v_cvt_pk_bf16_f32 v225, v18, v19
	v_cvt_pk_bf16_f32 v226, v12, v13
	v_cvt_pk_bf16_f32 v227, v14, v15
	global_store_dwordx4 v187, v[224:227], s[34:35]
	v_cvt_pk_bf16_f32 v228, v8, v9
	v_cvt_pk_bf16_f32 v229, v10, v11
	v_cvt_pk_bf16_f32 v230, v4, v5
	v_cvt_pk_bf16_f32 v231, v6, v7
	global_store_dwordx4 v187, v[228:231], s[34:35] offset:64
	s_branch .Lp1e_done
.Lp1e_gelu:
	s_mov_b32 s38, 0x3d372713
	s_mov_b32 s39, 0x3d372713
	s_mov_b32 s40, 0xc0135761
	s_mov_b32 s41, 0xc0135761
	v_pk_mul_f32 v[190:191], v[128:129], s[38:39]
	v_pk_mul_f32 v[192:193], v[130:131], s[38:39]
	v_pk_mul_f32 v[194:195], v[124:125], s[38:39]
	v_pk_mul_f32 v[196:197], v[126:127], s[38:39]
	v_pk_mul_f32 v[190:191], v[128:129], v[190:191]
	v_pk_mul_f32 v[192:193], v[130:131], v[192:193]
	v_pk_mul_f32 v[194:195], v[124:125], v[194:195]
	v_pk_mul_f32 v[196:197], v[126:127], v[196:197]
	v_pk_fma_f32 v[190:191], v[128:129], v[190:191], v[128:129]
	v_pk_fma_f32 v[192:193], v[130:131], v[192:193], v[130:131]
	v_pk_fma_f32 v[194:195], v[124:125], v[194:195], v[124:125]
	v_pk_fma_f32 v[196:197], v[126:127], v[196:197], v[126:127]
	v_pk_mul_f32 v[190:191], v[190:191], s[40:41]
	v_pk_mul_f32 v[192:193], v[192:193], s[40:41]
	v_pk_mul_f32 v[194:195], v[194:195], s[40:41]
	v_pk_mul_f32 v[196:197], v[196:197], s[40:41]
	v_exp_f32_e32 v190, v190
	v_exp_f32_e32 v191, v191
	v_exp_f32_e32 v192, v192
	v_exp_f32_e32 v193, v193
	v_exp_f32_e32 v194, v194
	v_exp_f32_e32 v195, v195
	v_exp_f32_e32 v196, v196
	v_exp_f32_e32 v197, v197
	v_pk_add_f32 v[190:191], v[190:191], s[42:43]
	v_pk_add_f32 v[192:193], v[192:193], s[42:43]
	v_pk_add_f32 v[194:195], v[194:195], s[42:43]
	v_pk_add_f32 v[196:197], v[196:197], s[42:43]
	v_rcp_f32_e32 v190, v190
	v_rcp_f32_e32 v191, v191
	v_rcp_f32_e32 v192, v192
	v_rcp_f32_e32 v193, v193
	v_rcp_f32_e32 v194, v194
	v_rcp_f32_e32 v195, v195
	v_rcp_f32_e32 v196, v196
	v_rcp_f32_e32 v197, v197
	v_pk_mul_f32 v[190:191], v[128:129], v[190:191]
	v_pk_mul_f32 v[192:193], v[130:131], v[192:193]
	v_pk_mul_f32 v[194:195], v[124:125], v[194:195]
	v_pk_mul_f32 v[196:197], v[126:127], v[196:197]
	v_cvt_pk_bf16_f32 v206, v190, v191
	v_cvt_pk_bf16_f32 v207, v192, v193
	v_cvt_pk_bf16_f32 v208, v194, v195
	v_cvt_pk_bf16_f32 v209, v196, v197
	global_store_dwordx4 v186, v[206:209], s[34:35]
	v_pk_mul_f32 v[198:199], v[120:121], s[38:39]
	v_pk_mul_f32 v[200:201], v[122:123], s[38:39]
	v_pk_mul_f32 v[202:203], v[116:117], s[38:39]
	v_pk_mul_f32 v[204:205], v[118:119], s[38:39]
	v_pk_mul_f32 v[198:199], v[120:121], v[198:199]
	v_pk_mul_f32 v[200:201], v[122:123], v[200:201]
	v_pk_mul_f32 v[202:203], v[116:117], v[202:203]
	v_pk_mul_f32 v[204:205], v[118:119], v[204:205]
	v_pk_fma_f32 v[198:199], v[120:121], v[198:199], v[120:121]
	v_pk_fma_f32 v[200:201], v[122:123], v[200:201], v[122:123]
	v_pk_fma_f32 v[202:203], v[116:117], v[202:203], v[116:117]
	v_pk_fma_f32 v[204:205], v[118:119], v[204:205], v[118:119]
	v_pk_mul_f32 v[198:199], v[198:199], s[40:41]
	v_pk_mul_f32 v[200:201], v[200:201], s[40:41]
	v_pk_mul_f32 v[202:203], v[202:203], s[40:41]
	v_pk_mul_f32 v[204:205], v[204:205], s[40:41]
	v_exp_f32_e32 v198, v198
	v_exp_f32_e32 v199, v199
	v_exp_f32_e32 v200, v200
	v_exp_f32_e32 v201, v201
	v_exp_f32_e32 v202, v202
	v_exp_f32_e32 v203, v203
	v_exp_f32_e32 v204, v204
	v_exp_f32_e32 v205, v205
	v_pk_add_f32 v[198:199], v[198:199], s[42:43]
	v_pk_add_f32 v[200:201], v[200:201], s[42:43]
	v_pk_add_f32 v[202:203], v[202:203], s[42:43]
	v_pk_add_f32 v[204:205], v[204:205], s[42:43]
	v_rcp_f32_e32 v198, v198
	v_rcp_f32_e32 v199, v199
	v_rcp_f32_e32 v200, v200
	v_rcp_f32_e32 v201, v201
	v_rcp_f32_e32 v202, v202
	v_rcp_f32_e32 v203, v203
	v_rcp_f32_e32 v204, v204
	v_rcp_f32_e32 v205, v205
	v_pk_mul_f32 v[198:199], v[120:121], v[198:199]
	v_pk_mul_f32 v[200:201], v[122:123], v[200:201]
	v_pk_mul_f32 v[202:203], v[116:117], v[202:203]
	v_pk_mul_f32 v[204:205], v[118:119], v[204:205]
	v_cvt_pk_bf16_f32 v218, v198, v199
	v_cvt_pk_bf16_f32 v219, v200, v201
	v_cvt_pk_bf16_f32 v220, v202, v203
	v_cvt_pk_bf16_f32 v221, v204, v205
	global_store_dwordx4 v186, v[218:221], s[34:35] offset:64
	v_add_u32_e32 v187, 0x8000, v186
	v_pk_mul_f32 v[190:191], v[112:113], s[38:39]
	v_pk_mul_f32 v[192:193], v[114:115], s[38:39]
	v_pk_mul_f32 v[194:195], v[108:109], s[38:39]
	v_pk_mul_f32 v[196:197], v[110:111], s[38:39]
	v_pk_mul_f32 v[190:191], v[112:113], v[190:191]
; __device__ __forceinline__ float fast_rcp(float x) { return __builtin_amdgcn_rcpf(x); }
; __device__ __forceinline__ float fast_exp2(float x) { return __builtin_amdgcn_exp2f(x); }
; __device__ __forceinline__ f32x4 sigm4(f32x4 v) { return (f32x4){sigmoid_f(v[0]), sigmoid_f(v[1]), sigmoid_f(v[2]), sigmoid_f(v[3])}; }
; __device__ __forceinline__ u32x4 pack8(f32x4 a, f32x4 b) { u32x4 w; w.x = cvt_pk_bf16(a[0], a[1]); w.y = cvt_pk_bf16(a[2], a[3]); w.z = cvt_pk_bf16(b[0], b[1]); w.w = cvt_pk_bf16(b[2], b[3]); return w; }
; __device__ __forceinline__ float gelu_tanh(float x) { const float t = x + 0.044715f * x * x * x; return x * fast_rcp(1.0f + fast_exp2(-2.3022081981f * t)); }
; __device__ __forceinline__ f32x4 gelu4(f32x4 v) { return (f32x4){gelu_tanh(v[0]), gelu_tanh(v[1]), gelu_tanh(v[2]), gelu_tanh(v[3])}; }
;     __device__ __forceinline__ void operator()(f32x4 (&acc)[2][2][4][2], const Unit& u, int wr, int wc, int fr, int fq) const {
;     ...
;                     for (int bj = 0; bj < 2; ++bj) {
;                         f32x4 v0 = acc[ai][bj][m][0] * rstd, v1 = acc[ai][bj][m][1] * rstd;
;                         if (mode == 3) { u32x2 w; w.x = gate_q4(sigm4(v0)); w.y = gate_q4(sigm4(v1)); *(u32x2*)((unsigned char*)Gt + (size_t)row * 4096 + col0 + bj * 32) = w; continue; }
;                         if (mode == 0) { v0 = gelu4(v0); v1 = gelu4(v1); }
;                         *(u32x4*)(rowp + bj * 32) = pack8(v0, v1);
	v_pk_mul_f32 v[192:193], v[114:115], v[192:193]
	v_pk_mul_f32 v[194:195], v[108:109], v[194:195]
	v_pk_mul_f32 v[196:197], v[110:111], v[196:197]
	v_pk_fma_f32 v[190:191], v[112:113], v[190:191], v[112:113]
	v_pk_fma_f32 v[192:193], v[114:115], v[192:193], v[114:115]
	v_pk_fma_f32 v[194:195], v[108:109], v[194:195], v[108:109]
	v_pk_fma_f32 v[196:197], v[110:111], v[196:197], v[110:111]
	v_pk_mul_f32 v[190:191], v[190:191], s[40:41]
	v_pk_mul_f32 v[192:193], v[192:193], s[40:41]
	v_pk_mul_f32 v[194:195], v[194:195], s[40:41]
	v_pk_mul_f32 v[196:197], v[196:197], s[40:41]
	v_exp_f32_e32 v190, v190
	v_exp_f32_e32 v191, v191
	v_exp_f32_e32 v192, v192
	v_exp_f32_e32 v193, v193
	v_exp_f32_e32 v194, v194
	v_exp_f32_e32 v195, v195
	v_exp_f32_e32 v196, v196
	v_exp_f32_e32 v197, v197
	v_pk_add_f32 v[190:191], v[190:191], s[42:43]
	v_pk_add_f32 v[192:193], v[192:193], s[42:43]
	v_pk_add_f32 v[194:195], v[194:195], s[42:43]
	v_pk_add_f32 v[196:197], v[196:197], s[42:43]
	v_rcp_f32_e32 v190, v190
	v_rcp_f32_e32 v191, v191
	v_rcp_f32_e32 v192, v192
	v_rcp_f32_e32 v193, v193
	v_rcp_f32_e32 v194, v194
	v_rcp_f32_e32 v195, v195
	v_rcp_f32_e32 v196, v196
	v_rcp_f32_e32 v197, v197
	v_pk_mul_f32 v[190:191], v[112:113], v[190:191]
	v_pk_mul_f32 v[192:193], v[114:115], v[192:193]
	v_pk_mul_f32 v[194:195], v[108:109], v[194:195]
	v_pk_mul_f32 v[196:197], v[110:111], v[196:197]
	v_cvt_pk_bf16_f32 v224, v190, v191
	v_cvt_pk_bf16_f32 v225, v192, v193
	v_cvt_pk_bf16_f32 v226, v194, v195
	v_cvt_pk_bf16_f32 v227, v196, v197
	global_store_dwordx4 v187, v[224:227], s[34:35]
	v_pk_mul_f32 v[198:199], v[104:105], s[38:39]
	v_pk_mul_f32 v[200:201], v[106:107], s[38:39]
	v_pk_mul_f32 v[202:203], v[100:101], s[38:39]
	v_pk_mul_f32 v[204:205], v[102:103], s[38:39]
	v_pk_mul_f32 v[198:199], v[104:105], v[198:199]
	v_pk_mul_f32 v[200:201], v[106:107], v[200:201]
	v_pk_mul_f32 v[202:203], v[100:101], v[202:203]
	v_pk_mul_f32 v[204:205], v[102:103], v[204:205]
	v_pk_fma_f32 v[198:199], v[104:105], v[198:199], v[104:105]
	v_pk_fma_f32 v[200:201], v[106:107], v[200:201], v[106:107]
	v_pk_fma_f32 v[202:203], v[100:101], v[202:203], v[100:101]
	v_pk_fma_f32 v[204:205], v[102:103], v[204:205], v[102:103]
	v_pk_mul_f32 v[198:199], v[198:199], s[40:41]
	v_pk_mul_f32 v[200:201], v[200:201], s[40:41]
	v_pk_mul_f32 v[202:203], v[202:203], s[40:41]
	v_pk_mul_f32 v[204:205], v[204:205], s[40:41]
	v_exp_f32_e32 v198, v198
	v_exp_f32_e32 v199, v199
	v_exp_f32_e32 v200, v200
	v_exp_f32_e32 v201, v201
	v_exp_f32_e32 v202, v202
	v_exp_f32_e32 v203, v203
	v_exp_f32_e32 v204, v204
	v_exp_f32_e32 v205, v205
	v_pk_add_f32 v[198:199], v[198:199], s[42:43]
	v_pk_add_f32 v[200:201], v[200:201], s[42:43]
	v_pk_add_f32 v[202:203], v[202:203], s[42:43]
	v_pk_add_f32 v[204:205], v[204:205], s[42:43]
	v_rcp_f32_e32 v198, v198
	v_rcp_f32_e32 v199, v199
	v_rcp_f32_e32 v200, v200
	v_rcp_f32_e32 v201, v201
	v_rcp_f32_e32 v202, v202
	v_rcp_f32_e32 v203, v203
	v_rcp_f32_e32 v204, v204
	v_rcp_f32_e32 v205, v205
	v_pk_mul_f32 v[198:199], v[104:105], v[198:199]
	v_pk_mul_f32 v[200:201], v[106:107], v[200:201]
	v_pk_mul_f32 v[202:203], v[100:101], v[202:203]
	v_pk_mul_f32 v[204:205], v[102:103], v[204:205]
	v_cvt_pk_bf16_f32 v228, v198, v199
	v_cvt_pk_bf16_f32 v229, v200, v201
	v_cvt_pk_bf16_f32 v230, v202, v203
	v_cvt_pk_bf16_f32 v231, v204, v205
	global_store_dwordx4 v187, v[228:231], s[34:35] offset:64
	v_add_u32_e32 v187, 0x10000, v186
	v_pk_mul_f32 v[190:191], v[96:97], s[38:39]
	v_pk_mul_f32 v[192:193], v[98:99], s[38:39]
	v_pk_mul_f32 v[194:195], v[92:93], s[38:39]
	v_pk_mul_f32 v[196:197], v[94:95], s[38:39]
	v_pk_mul_f32 v[190:191], v[96:97], v[190:191]
	v_pk_mul_f32 v[192:193], v[98:99], v[192:193]
	v_pk_mul_f32 v[194:195], v[92:93], v[194:195]
	v_pk_mul_f32 v[196:197], v[94:95], v[196:197]
	v_pk_fma_f32 v[190:191], v[96:97], v[190:191], v[96:97]
	v_pk_fma_f32 v[192:193], v[98:99], v[192:193], v[98:99]
	v_pk_fma_f32 v[194:195], v[92:93], v[194:195], v[92:93]
	v_pk_fma_f32 v[196:197], v[94:95], v[196:197], v[94:95]
	v_pk_mul_f32 v[190:191], v[190:191], s[40:41]
	v_pk_mul_f32 v[192:193], v[192:193], s[40:41]
	v_pk_mul_f32 v[194:195], v[194:195], s[40:41]
	v_pk_mul_f32 v[196:197], v[196:197], s[40:41]
	v_exp_f32_e32 v190, v190
	v_exp_f32_e32 v191, v191
	v_exp_f32_e32 v192, v192
	v_exp_f32_e32 v193, v193
	v_exp_f32_e32 v194, v194
	v_exp_f32_e32 v195, v195
	v_exp_f32_e32 v196, v196
	v_exp_f32_e32 v197, v197
	v_pk_add_f32 v[190:191], v[190:191], s[42:43]
	v_pk_add_f32 v[192:193], v[192:193], s[42:43]
	v_pk_add_f32 v[194:195], v[194:195], s[42:43]
	v_pk_add_f32 v[196:197], v[196:197], s[42:43]
	v_rcp_f32_e32 v190, v190
	v_rcp_f32_e32 v191, v191
	v_rcp_f32_e32 v192, v192
	v_rcp_f32_e32 v193, v193
	v_rcp_f32_e32 v194, v194
	v_rcp_f32_e32 v195, v195
	v_rcp_f32_e32 v196, v196
	v_rcp_f32_e32 v197, v197
	v_pk_mul_f32 v[190:191], v[96:97], v[190:191]
	v_pk_mul_f32 v[192:193], v[98:99], v[192:193]
	v_pk_mul_f32 v[194:195], v[92:93], v[194:195]
	v_pk_mul_f32 v[196:197], v[94:95], v[196:197]
	v_cvt_pk_bf16_f32 v206, v190, v191
	v_cvt_pk_bf16_f32 v207, v192, v193
	v_cvt_pk_bf16_f32 v208, v194, v195
	v_cvt_pk_bf16_f32 v209, v196, v197
	global_store_dwordx4 v187, v[206:209], s[34:35]
	v_pk_mul_f32 v[198:199], v[88:89], s[38:39]
	v_pk_mul_f32 v[200:201], v[90:91], s[38:39]
	v_pk_mul_f32 v[202:203], v[84:85], s[38:39]
	v_pk_mul_f32 v[204:205], v[86:87], s[38:39]
	v_pk_mul_f32 v[198:199], v[88:89], v[198:199]
	v_pk_mul_f32 v[200:201], v[90:91], v[200:201]
	v_pk_mul_f32 v[202:203], v[84:85], v[202:203]
	v_pk_mul_f32 v[204:205], v[86:87], v[204:205]
	v_pk_fma_f32 v[198:199], v[88:89], v[198:199], v[88:89]
; __device__ __forceinline__ float fast_rcp(float x) { return __builtin_amdgcn_rcpf(x); }
; __device__ __forceinline__ float fast_exp2(float x) { return __builtin_amdgcn_exp2f(x); }
; __device__ __forceinline__ f32x4 sigm4(f32x4 v) { return (f32x4){sigmoid_f(v[0]), sigmoid_f(v[1]), sigmoid_f(v[2]), sigmoid_f(v[3])}; }
; __device__ __forceinline__ u32x4 pack8(f32x4 a, f32x4 b) { u32x4 w; w.x = cvt_pk_bf16(a[0], a[1]); w.y = cvt_pk_bf16(a[2], a[3]); w.z = cvt_pk_bf16(b[0], b[1]); w.w = cvt_pk_bf16(b[2], b[3]); return w; }
; __device__ __forceinline__ float gelu_tanh(float x) { const float t = x + 0.044715f * x * x * x; return x * fast_rcp(1.0f + fast_exp2(-2.3022081981f * t)); }
; __device__ __forceinline__ f32x4 gelu4(f32x4 v) { return (f32x4){gelu_tanh(v[0]), gelu_tanh(v[1]), gelu_tanh(v[2]), gelu_tanh(v[3])}; }
;     __device__ __forceinline__ void operator()(f32x4 (&acc)[2][2][4][2], const Unit& u, int wr, int wc, int fr, int fq) const {
;     ...
;                     for (int bj = 0; bj < 2; ++bj) {
;                         f32x4 v0 = acc[ai][bj][m][0] * rstd, v1 = acc[ai][bj][m][1] * rstd;
;                         if (mode == 3) { u32x2 w; w.x = gate_q4(sigm4(v0)); w.y = gate_q4(sigm4(v1)); *(u32x2*)((unsigned char*)Gt + (size_t)row * 4096 + col0 + bj * 32) = w; continue; }
;                         if (mode == 0) { v0 = gelu4(v0); v1 = gelu4(v1); }
;                         *(u32x4*)(rowp + bj * 32) = pack8(v0, v1);
	v_pk_fma_f32 v[200:201], v[90:91], v[200:201], v[90:91]
	v_pk_fma_f32 v[202:203], v[84:85], v[202:203], v[84:85]
	v_pk_fma_f32 v[204:205], v[86:87], v[204:205], v[86:87]
	v_pk_mul_f32 v[198:199], v[198:199], s[40:41]
	v_pk_mul_f32 v[200:201], v[200:201], s[40:41]
	v_pk_mul_f32 v[202:203], v[202:203], s[40:41]
	v_pk_mul_f32 v[204:205], v[204:205], s[40:41]
	v_exp_f32_e32 v198, v198
	v_exp_f32_e32 v199, v199
	v_exp_f32_e32 v200, v200
	v_exp_f32_e32 v201, v201
	v_exp_f32_e32 v202, v202
	v_exp_f32_e32 v203, v203
	v_exp_f32_e32 v204, v204
	v_exp_f32_e32 v205, v205
	v_pk_add_f32 v[198:199], v[198:199], s[42:43]
	v_pk_add_f32 v[200:201], v[200:201], s[42:43]
	v_pk_add_f32 v[202:203], v[202:203], s[42:43]
	v_pk_add_f32 v[204:205], v[204:205], s[42:43]
	v_rcp_f32_e32 v198, v198
	v_rcp_f32_e32 v199, v199
	v_rcp_f32_e32 v200, v200
	v_rcp_f32_e32 v201, v201
	v_rcp_f32_e32 v202, v202
	v_rcp_f32_e32 v203, v203
	v_rcp_f32_e32 v204, v204
	v_rcp_f32_e32 v205, v205
	v_pk_mul_f32 v[198:199], v[88:89], v[198:199]
	v_pk_mul_f32 v[200:201], v[90:91], v[200:201]
	v_pk_mul_f32 v[202:203], v[84:85], v[202:203]
	v_pk_mul_f32 v[204:205], v[86:87], v[204:205]
	v_cvt_pk_bf16_f32 v218, v198, v199
	v_cvt_pk_bf16_f32 v219, v200, v201
	v_cvt_pk_bf16_f32 v220, v202, v203
	v_cvt_pk_bf16_f32 v221, v204, v205
	global_store_dwordx4 v187, v[218:221], s[34:35] offset:64
	v_add_u32_e32 v187, 0x18000, v186
	v_pk_mul_f32 v[190:191], v[80:81], s[38:39]
	v_pk_mul_f32 v[192:193], v[82:83], s[38:39]
	v_pk_mul_f32 v[194:195], v[76:77], s[38:39]
	v_pk_mul_f32 v[196:197], v[78:79], s[38:39]
	v_pk_mul_f32 v[190:191], v[80:81], v[190:191]
	v_pk_mul_f32 v[192:193], v[82:83], v[192:193]
	v_pk_mul_f32 v[194:195], v[76:77], v[194:195]
	v_pk_mul_f32 v[196:197], v[78:79], v[196:197]
	v_pk_fma_f32 v[190:191], v[80:81], v[190:191], v[80:81]
	v_pk_fma_f32 v[192:193], v[82:83], v[192:193], v[82:83]
	v_pk_fma_f32 v[194:195], v[76:77], v[194:195], v[76:77]
	v_pk_fma_f32 v[196:197], v[78:79], v[196:197], v[78:79]
	v_pk_mul_f32 v[190:191], v[190:191], s[40:41]
	v_pk_mul_f32 v[192:193], v[192:193], s[40:41]
	v_pk_mul_f32 v[194:195], v[194:195], s[40:41]
	v_pk_mul_f32 v[196:197], v[196:197], s[40:41]
	v_exp_f32_e32 v190, v190
	v_exp_f32_e32 v191, v191
	v_exp_f32_e32 v192, v192
	v_exp_f32_e32 v193, v193
	v_exp_f32_e32 v194, v194
	v_exp_f32_e32 v195, v195
	v_exp_f32_e32 v196, v196
	v_exp_f32_e32 v197, v197
	v_pk_add_f32 v[190:191], v[190:191], s[42:43]
	v_pk_add_f32 v[192:193], v[192:193], s[42:43]
	v_pk_add_f32 v[194:195], v[194:195], s[42:43]
	v_pk_add_f32 v[196:197], v[196:197], s[42:43]
	v_rcp_f32_e32 v190, v190
	v_rcp_f32_e32 v191, v191
	v_rcp_f32_e32 v192, v192
	v_rcp_f32_e32 v193, v193
	v_rcp_f32_e32 v194, v194
	v_rcp_f32_e32 v195, v195
	v_rcp_f32_e32 v196, v196
	v_rcp_f32_e32 v197, v197
	v_pk_mul_f32 v[190:191], v[80:81], v[190:191]
	v_pk_mul_f32 v[192:193], v[82:83], v[192:193]
	v_pk_mul_f32 v[194:195], v[76:77], v[194:195]
	v_pk_mul_f32 v[196:197], v[78:79], v[196:197]
	v_cvt_pk_bf16_f32 v224, v190, v191
	v_cvt_pk_bf16_f32 v225, v192, v193
	v_cvt_pk_bf16_f32 v226, v194, v195
	v_cvt_pk_bf16_f32 v227, v196, v197
	global_store_dwordx4 v187, v[224:227], s[34:35]
	v_pk_mul_f32 v[198:199], v[72:73], s[38:39]
	v_pk_mul_f32 v[200:201], v[74:75], s[38:39]
	v_pk_mul_f32 v[202:203], v[68:69], s[38:39]
	v_pk_mul_f32 v[204:205], v[70:71], s[38:39]
	v_pk_mul_f32 v[198:199], v[72:73], v[198:199]
	v_pk_mul_f32 v[200:201], v[74:75], v[200:201]
	v_pk_mul_f32 v[202:203], v[68:69], v[202:203]
	v_pk_mul_f32 v[204:205], v[70:71], v[204:205]
	v_pk_fma_f32 v[198:199], v[72:73], v[198:199], v[72:73]
	v_pk_fma_f32 v[200:201], v[74:75], v[200:201], v[74:75]
	v_pk_fma_f32 v[202:203], v[68:69], v[202:203], v[68:69]
	v_pk_fma_f32 v[204:205], v[70:71], v[204:205], v[70:71]
	v_pk_mul_f32 v[198:199], v[198:199], s[40:41]
	v_pk_mul_f32 v[200:201], v[200:201], s[40:41]
	v_pk_mul_f32 v[202:203], v[202:203], s[40:41]
	v_pk_mul_f32 v[204:205], v[204:205], s[40:41]
	v_exp_f32_e32 v198, v198
	v_exp_f32_e32 v199, v199
	v_exp_f32_e32 v200, v200
	v_exp_f32_e32 v201, v201
	v_exp_f32_e32 v202, v202
	v_exp_f32_e32 v203, v203
	v_exp_f32_e32 v204, v204
	v_exp_f32_e32 v205, v205
	v_pk_add_f32 v[198:199], v[198:199], s[42:43]
	v_pk_add_f32 v[200:201], v[200:201], s[42:43]
	v_pk_add_f32 v[202:203], v[202:203], s[42:43]
	v_pk_add_f32 v[204:205], v[204:205], s[42:43]
	v_rcp_f32_e32 v198, v198
	v_rcp_f32_e32 v199, v199
	v_rcp_f32_e32 v200, v200
	v_rcp_f32_e32 v201, v201
	v_rcp_f32_e32 v202, v202
	v_rcp_f32_e32 v203, v203
	v_rcp_f32_e32 v204, v204
	v_rcp_f32_e32 v205, v205
	v_pk_mul_f32 v[198:199], v[72:73], v[198:199]
	v_pk_mul_f32 v[200:201], v[74:75], v[200:201]
	v_pk_mul_f32 v[202:203], v[68:69], v[202:203]
	v_pk_mul_f32 v[204:205], v[70:71], v[204:205]
	v_cvt_pk_bf16_f32 v228, v198, v199
	v_cvt_pk_bf16_f32 v229, v200, v201
	v_cvt_pk_bf16_f32 v230, v202, v203
	v_cvt_pk_bf16_f32 v231, v204, v205
	global_store_dwordx4 v187, v[228:231], s[34:35] offset:64
	v_add_u32_e32 v187, 0x40000, v186
	v_pk_mul_f32 v[190:191], v[64:65], s[38:39]
	v_pk_mul_f32 v[192:193], v[66:67], s[38:39]
	v_pk_mul_f32 v[194:195], v[60:61], s[38:39]
	v_pk_mul_f32 v[196:197], v[62:63], s[38:39]
	v_pk_mul_f32 v[190:191], v[64:65], v[190:191]
	v_pk_mul_f32 v[192:193], v[66:67], v[192:193]
	v_pk_mul_f32 v[194:195], v[60:61], v[194:195]
	v_pk_mul_f32 v[196:197], v[62:63], v[196:197]
	v_pk_fma_f32 v[190:191], v[64:65], v[190:191], v[64:65]
	v_pk_fma_f32 v[192:193], v[66:67], v[192:193], v[66:67]
	v_pk_fma_f32 v[194:195], v[60:61], v[194:195], v[60:61]
	v_pk_fma_f32 v[196:197], v[62:63], v[196:197], v[62:63]
	v_pk_mul_f32 v[190:191], v[190:191], s[40:41]
	v_pk_mul_f32 v[192:193], v[192:193], s[40:41]
; __device__ __forceinline__ float fast_rcp(float x) { return __builtin_amdgcn_rcpf(x); }
; __device__ __forceinline__ float fast_exp2(float x) { return __builtin_amdgcn_exp2f(x); }
; __device__ __forceinline__ f32x4 sigm4(f32x4 v) { return (f32x4){sigmoid_f(v[0]), sigmoid_f(v[1]), sigmoid_f(v[2]), sigmoid_f(v[3])}; }
; __device__ __forceinline__ u32x4 pack8(f32x4 a, f32x4 b) { u32x4 w; w.x = cvt_pk_bf16(a[0], a[1]); w.y = cvt_pk_bf16(a[2], a[3]); w.z = cvt_pk_bf16(b[0], b[1]); w.w = cvt_pk_bf16(b[2], b[3]); return w; }
; __device__ __forceinline__ float gelu_tanh(float x) { const float t = x + 0.044715f * x * x * x; return x * fast_rcp(1.0f + fast_exp2(-2.3022081981f * t)); }
; __device__ __forceinline__ f32x4 gelu4(f32x4 v) { return (f32x4){gelu_tanh(v[0]), gelu_tanh(v[1]), gelu_tanh(v[2]), gelu_tanh(v[3])}; }
;     __device__ __forceinline__ void operator()(f32x4 (&acc)[2][2][4][2], const Unit& u, int wr, int wc, int fr, int fq) const {
;     ...
;                     for (int bj = 0; bj < 2; ++bj) {
;                         f32x4 v0 = acc[ai][bj][m][0] * rstd, v1 = acc[ai][bj][m][1] * rstd;
;                         if (mode == 3) { u32x2 w; w.x = gate_q4(sigm4(v0)); w.y = gate_q4(sigm4(v1)); *(u32x2*)((unsigned char*)Gt + (size_t)row * 4096 + col0 + bj * 32) = w; continue; }
;                         if (mode == 0) { v0 = gelu4(v0); v1 = gelu4(v1); }
;                         *(u32x4*)(rowp + bj * 32) = pack8(v0, v1);
	v_pk_mul_f32 v[194:195], v[194:195], s[40:41]
	v_pk_mul_f32 v[196:197], v[196:197], s[40:41]
	v_exp_f32_e32 v190, v190
	v_exp_f32_e32 v191, v191
	v_exp_f32_e32 v192, v192
	v_exp_f32_e32 v193, v193
	v_exp_f32_e32 v194, v194
	v_exp_f32_e32 v195, v195
	v_exp_f32_e32 v196, v196
	v_exp_f32_e32 v197, v197
	v_pk_add_f32 v[190:191], v[190:191], s[42:43]
	v_pk_add_f32 v[192:193], v[192:193], s[42:43]
	v_pk_add_f32 v[194:195], v[194:195], s[42:43]
	v_pk_add_f32 v[196:197], v[196:197], s[42:43]
	v_rcp_f32_e32 v190, v190
	v_rcp_f32_e32 v191, v191
	v_rcp_f32_e32 v192, v192
	v_rcp_f32_e32 v193, v193
	v_rcp_f32_e32 v194, v194
	v_rcp_f32_e32 v195, v195
	v_rcp_f32_e32 v196, v196
	v_rcp_f32_e32 v197, v197
	v_pk_mul_f32 v[190:191], v[64:65], v[190:191]
	v_pk_mul_f32 v[192:193], v[66:67], v[192:193]
	v_pk_mul_f32 v[194:195], v[60:61], v[194:195]
	v_pk_mul_f32 v[196:197], v[62:63], v[196:197]
	v_cvt_pk_bf16_f32 v206, v190, v191
	v_cvt_pk_bf16_f32 v207, v192, v193
	v_cvt_pk_bf16_f32 v208, v194, v195
	v_cvt_pk_bf16_f32 v209, v196, v197
	global_store_dwordx4 v187, v[206:209], s[34:35]
	v_pk_mul_f32 v[198:199], v[56:57], s[38:39]
	v_pk_mul_f32 v[200:201], v[58:59], s[38:39]
	v_pk_mul_f32 v[202:203], v[52:53], s[38:39]
	v_pk_mul_f32 v[204:205], v[54:55], s[38:39]
	v_pk_mul_f32 v[198:199], v[56:57], v[198:199]
	v_pk_mul_f32 v[200:201], v[58:59], v[200:201]
	v_pk_mul_f32 v[202:203], v[52:53], v[202:203]
	v_pk_mul_f32 v[204:205], v[54:55], v[204:205]
	v_pk_fma_f32 v[198:199], v[56:57], v[198:199], v[56:57]
	v_pk_fma_f32 v[200:201], v[58:59], v[200:201], v[58:59]
	v_pk_fma_f32 v[202:203], v[52:53], v[202:203], v[52:53]
	v_pk_fma_f32 v[204:205], v[54:55], v[204:205], v[54:55]
	v_pk_mul_f32 v[198:199], v[198:199], s[40:41]
	v_pk_mul_f32 v[200:201], v[200:201], s[40:41]
	v_pk_mul_f32 v[202:203], v[202:203], s[40:41]
	v_pk_mul_f32 v[204:205], v[204:205], s[40:41]
	v_exp_f32_e32 v198, v198
	v_exp_f32_e32 v199, v199
	v_exp_f32_e32 v200, v200
	v_exp_f32_e32 v201, v201
	v_exp_f32_e32 v202, v202
	v_exp_f32_e32 v203, v203
	v_exp_f32_e32 v204, v204
	v_exp_f32_e32 v205, v205
	v_pk_add_f32 v[198:199], v[198:199], s[42:43]
	v_pk_add_f32 v[200:201], v[200:201], s[42:43]
	v_pk_add_f32 v[202:203], v[202:203], s[42:43]
	v_pk_add_f32 v[204:205], v[204:205], s[42:43]
	v_rcp_f32_e32 v198, v198
	v_rcp_f32_e32 v199, v199
	v_rcp_f32_e32 v200, v200
	v_rcp_f32_e32 v201, v201
	v_rcp_f32_e32 v202, v202
	v_rcp_f32_e32 v203, v203
	v_rcp_f32_e32 v204, v204
	v_rcp_f32_e32 v205, v205
	v_pk_mul_f32 v[198:199], v[56:57], v[198:199]
	v_pk_mul_f32 v[200:201], v[58:59], v[200:201]
	v_pk_mul_f32 v[202:203], v[52:53], v[202:203]
	v_pk_mul_f32 v[204:205], v[54:55], v[204:205]
	v_cvt_pk_bf16_f32 v218, v198, v199
	v_cvt_pk_bf16_f32 v219, v200, v201
	v_cvt_pk_bf16_f32 v220, v202, v203
	v_cvt_pk_bf16_f32 v221, v204, v205
	global_store_dwordx4 v187, v[218:221], s[34:35] offset:64
	v_add_u32_e32 v187, 0x48000, v186
	v_pk_mul_f32 v[190:191], v[48:49], s[38:39]
	v_pk_mul_f32 v[192:193], v[50:51], s[38:39]
	v_pk_mul_f32 v[194:195], v[44:45], s[38:39]
	v_pk_mul_f32 v[196:197], v[46:47], s[38:39]
	v_pk_mul_f32 v[190:191], v[48:49], v[190:191]
	v_pk_mul_f32 v[192:193], v[50:51], v[192:193]
	v_pk_mul_f32 v[194:195], v[44:45], v[194:195]
	v_pk_mul_f32 v[196:197], v[46:47], v[196:197]
	v_pk_fma_f32 v[190:191], v[48:49], v[190:191], v[48:49]
	v_pk_fma_f32 v[192:193], v[50:51], v[192:193], v[50:51]
	v_pk_fma_f32 v[194:195], v[44:45], v[194:195], v[44:45]
	v_pk_fma_f32 v[196:197], v[46:47], v[196:197], v[46:47]
	v_pk_mul_f32 v[190:191], v[190:191], s[40:41]
	v_pk_mul_f32 v[192:193], v[192:193], s[40:41]
	v_pk_mul_f32 v[194:195], v[194:195], s[40:41]
	v_pk_mul_f32 v[196:197], v[196:197], s[40:41]
	v_exp_f32_e32 v190, v190
	v_exp_f32_e32 v191, v191
	v_exp_f32_e32 v192, v192
	v_exp_f32_e32 v193, v193
	v_exp_f32_e32 v194, v194
	v_exp_f32_e32 v195, v195
	v_exp_f32_e32 v196, v196
	v_exp_f32_e32 v197, v197
	v_pk_add_f32 v[190:191], v[190:191], s[42:43]
	v_pk_add_f32 v[192:193], v[192:193], s[42:43]
	v_pk_add_f32 v[194:195], v[194:195], s[42:43]
	v_pk_add_f32 v[196:197], v[196:197], s[42:43]
	v_rcp_f32_e32 v190, v190
	v_rcp_f32_e32 v191, v191
	v_rcp_f32_e32 v192, v192
	v_rcp_f32_e32 v193, v193
	v_rcp_f32_e32 v194, v194
	v_rcp_f32_e32 v195, v195
	v_rcp_f32_e32 v196, v196
	v_rcp_f32_e32 v197, v197
	v_pk_mul_f32 v[190:191], v[48:49], v[190:191]
	v_pk_mul_f32 v[192:193], v[50:51], v[192:193]
	v_pk_mul_f32 v[194:195], v[44:45], v[194:195]
	v_pk_mul_f32 v[196:197], v[46:47], v[196:197]
	v_cvt_pk_bf16_f32 v224, v190, v191
	v_cvt_pk_bf16_f32 v225, v192, v193
	v_cvt_pk_bf16_f32 v226, v194, v195
	v_cvt_pk_bf16_f32 v227, v196, v197
	global_store_dwordx4 v187, v[224:227], s[34:35]
	v_pk_mul_f32 v[198:199], v[40:41], s[38:39]
	v_pk_mul_f32 v[200:201], v[42:43], s[38:39]
	v_pk_mul_f32 v[202:203], v[36:37], s[38:39]
	v_pk_mul_f32 v[204:205], v[38:39], s[38:39]
	v_pk_mul_f32 v[198:199], v[40:41], v[198:199]
	v_pk_mul_f32 v[200:201], v[42:43], v[200:201]
	v_pk_mul_f32 v[202:203], v[36:37], v[202:203]
	v_pk_mul_f32 v[204:205], v[38:39], v[204:205]
	v_pk_fma_f32 v[198:199], v[40:41], v[198:199], v[40:41]
	v_pk_fma_f32 v[200:201], v[42:43], v[200:201], v[42:43]
	v_pk_fma_f32 v[202:203], v[36:37], v[202:203], v[36:37]
	v_pk_fma_f32 v[204:205], v[38:39], v[204:205], v[38:39]
	v_pk_mul_f32 v[198:199], v[198:199], s[40:41]
	v_pk_mul_f32 v[200:201], v[200:201], s[40:41]
	v_pk_mul_f32 v[202:203], v[202:203], s[40:41]
	v_pk_mul_f32 v[204:205], v[204:205], s[40:41]
	v_exp_f32_e32 v198, v198
	v_exp_f32_e32 v199, v199
	v_exp_f32_e32 v200, v200
	v_exp_f32_e32 v201, v201
	v_exp_f32_e32 v202, v202
	v_exp_f32_e32 v203, v203
	v_exp_f32_e32 v204, v204
; __device__ __forceinline__ float fast_rcp(float x) { return __builtin_amdgcn_rcpf(x); }
; __device__ __forceinline__ float fast_exp2(float x) { return __builtin_amdgcn_exp2f(x); }
; __device__ __forceinline__ f32x4 sigm4(f32x4 v) { return (f32x4){sigmoid_f(v[0]), sigmoid_f(v[1]), sigmoid_f(v[2]), sigmoid_f(v[3])}; }
; __device__ __forceinline__ u32x4 pack8(f32x4 a, f32x4 b) { u32x4 w; w.x = cvt_pk_bf16(a[0], a[1]); w.y = cvt_pk_bf16(a[2], a[3]); w.z = cvt_pk_bf16(b[0], b[1]); w.w = cvt_pk_bf16(b[2], b[3]); return w; }
; __device__ __forceinline__ float gelu_tanh(float x) { const float t = x + 0.044715f * x * x * x; return x * fast_rcp(1.0f + fast_exp2(-2.3022081981f * t)); }
; __device__ __forceinline__ f32x4 gelu4(f32x4 v) { return (f32x4){gelu_tanh(v[0]), gelu_tanh(v[1]), gelu_tanh(v[2]), gelu_tanh(v[3])}; }
;     __device__ __forceinline__ void operator()(f32x4 (&acc)[2][2][4][2], const Unit& u, int wr, int wc, int fr, int fq) const {
;     ...
;                     for (int bj = 0; bj < 2; ++bj) {
;                         f32x4 v0 = acc[ai][bj][m][0] * rstd, v1 = acc[ai][bj][m][1] * rstd;
;                         if (mode == 3) { u32x2 w; w.x = gate_q4(sigm4(v0)); w.y = gate_q4(sigm4(v1)); *(u32x2*)((unsigned char*)Gt + (size_t)row * 4096 + col0 + bj * 32) = w; continue; }
;                         if (mode == 0) { v0 = gelu4(v0); v1 = gelu4(v1); }
;                         *(u32x4*)(rowp + bj * 32) = pack8(v0, v1);
	v_exp_f32_e32 v205, v205
	v_pk_add_f32 v[198:199], v[198:199], s[42:43]
	v_pk_add_f32 v[200:201], v[200:201], s[42:43]
	v_pk_add_f32 v[202:203], v[202:203], s[42:43]
	v_pk_add_f32 v[204:205], v[204:205], s[42:43]
	v_rcp_f32_e32 v198, v198
	v_rcp_f32_e32 v199, v199
	v_rcp_f32_e32 v200, v200
	v_rcp_f32_e32 v201, v201
	v_rcp_f32_e32 v202, v202
	v_rcp_f32_e32 v203, v203
	v_rcp_f32_e32 v204, v204
	v_rcp_f32_e32 v205, v205
	v_pk_mul_f32 v[198:199], v[40:41], v[198:199]
	v_pk_mul_f32 v[200:201], v[42:43], v[200:201]
	v_pk_mul_f32 v[202:203], v[36:37], v[202:203]
	v_pk_mul_f32 v[204:205], v[38:39], v[204:205]
	v_cvt_pk_bf16_f32 v228, v198, v199
	v_cvt_pk_bf16_f32 v229, v200, v201
	v_cvt_pk_bf16_f32 v230, v202, v203
	v_cvt_pk_bf16_f32 v231, v204, v205
	global_store_dwordx4 v187, v[228:231], s[34:35] offset:64
	v_add_u32_e32 v187, 0x50000, v186
	v_pk_mul_f32 v[190:191], v[32:33], s[38:39]
	v_pk_mul_f32 v[192:193], v[34:35], s[38:39]
	v_pk_mul_f32 v[194:195], v[28:29], s[38:39]
	v_pk_mul_f32 v[196:197], v[30:31], s[38:39]
	v_pk_mul_f32 v[190:191], v[32:33], v[190:191]
	v_pk_mul_f32 v[192:193], v[34:35], v[192:193]
	v_pk_mul_f32 v[194:195], v[28:29], v[194:195]
	v_pk_mul_f32 v[196:197], v[30:31], v[196:197]
	v_pk_fma_f32 v[190:191], v[32:33], v[190:191], v[32:33]
	v_pk_fma_f32 v[192:193], v[34:35], v[192:193], v[34:35]
	v_pk_fma_f32 v[194:195], v[28:29], v[194:195], v[28:29]
	v_pk_fma_f32 v[196:197], v[30:31], v[196:197], v[30:31]
	v_pk_mul_f32 v[190:191], v[190:191], s[40:41]
	v_pk_mul_f32 v[192:193], v[192:193], s[40:41]
	v_pk_mul_f32 v[194:195], v[194:195], s[40:41]
	v_pk_mul_f32 v[196:197], v[196:197], s[40:41]
	v_exp_f32_e32 v190, v190
	v_exp_f32_e32 v191, v191
	v_exp_f32_e32 v192, v192
	v_exp_f32_e32 v193, v193
	v_exp_f32_e32 v194, v194
	v_exp_f32_e32 v195, v195
	v_exp_f32_e32 v196, v196
	v_exp_f32_e32 v197, v197
	v_pk_add_f32 v[190:191], v[190:191], s[42:43]
	v_pk_add_f32 v[192:193], v[192:193], s[42:43]
	v_pk_add_f32 v[194:195], v[194:195], s[42:43]
	v_pk_add_f32 v[196:197], v[196:197], s[42:43]
	v_rcp_f32_e32 v190, v190
	v_rcp_f32_e32 v191, v191
	v_rcp_f32_e32 v192, v192
	v_rcp_f32_e32 v193, v193
	v_rcp_f32_e32 v194, v194
	v_rcp_f32_e32 v195, v195
	v_rcp_f32_e32 v196, v196
	v_rcp_f32_e32 v197, v197
	v_pk_mul_f32 v[190:191], v[32:33], v[190:191]
	v_pk_mul_f32 v[192:193], v[34:35], v[192:193]
	v_pk_mul_f32 v[194:195], v[28:29], v[194:195]
	v_pk_mul_f32 v[196:197], v[30:31], v[196:197]
	v_cvt_pk_bf16_f32 v206, v190, v191
	v_cvt_pk_bf16_f32 v207, v192, v193
	v_cvt_pk_bf16_f32 v208, v194, v195
	v_cvt_pk_bf16_f32 v209, v196, v197
	global_store_dwordx4 v187, v[206:209], s[34:35]
	v_pk_mul_f32 v[198:199], v[24:25], s[38:39]
	v_pk_mul_f32 v[200:201], v[26:27], s[38:39]
	v_pk_mul_f32 v[202:203], v[20:21], s[38:39]
	v_pk_mul_f32 v[204:205], v[22:23], s[38:39]
	v_pk_mul_f32 v[198:199], v[24:25], v[198:199]
	v_pk_mul_f32 v[200:201], v[26:27], v[200:201]
	v_pk_mul_f32 v[202:203], v[20:21], v[202:203]
	v_pk_mul_f32 v[204:205], v[22:23], v[204:205]
	v_pk_fma_f32 v[198:199], v[24:25], v[198:199], v[24:25]
	v_pk_fma_f32 v[200:201], v[26:27], v[200:201], v[26:27]
	v_pk_fma_f32 v[202:203], v[20:21], v[202:203], v[20:21]
	v_pk_fma_f32 v[204:205], v[22:23], v[204:205], v[22:23]
	v_pk_mul_f32 v[198:199], v[198:199], s[40:41]
	v_pk_mul_f32 v[200:201], v[200:201], s[40:41]
	v_pk_mul_f32 v[202:203], v[202:203], s[40:41]
	v_pk_mul_f32 v[204:205], v[204:205], s[40:41]
	v_exp_f32_e32 v198, v198
	v_exp_f32_e32 v199, v199
	v_exp_f32_e32 v200, v200
	v_exp_f32_e32 v201, v201
	v_exp_f32_e32 v202, v202
	v_exp_f32_e32 v203, v203
	v_exp_f32_e32 v204, v204
	v_exp_f32_e32 v205, v205
	v_pk_add_f32 v[198:199], v[198:199], s[42:43]
	v_pk_add_f32 v[200:201], v[200:201], s[42:43]
	v_pk_add_f32 v[202:203], v[202:203], s[42:43]
	v_pk_add_f32 v[204:205], v[204:205], s[42:43]
	v_rcp_f32_e32 v198, v198
	v_rcp_f32_e32 v199, v199
	v_rcp_f32_e32 v200, v200
	v_rcp_f32_e32 v201, v201
	v_rcp_f32_e32 v202, v202
	v_rcp_f32_e32 v203, v203
	v_rcp_f32_e32 v204, v204
	v_rcp_f32_e32 v205, v205
	v_pk_mul_f32 v[198:199], v[24:25], v[198:199]
	v_pk_mul_f32 v[200:201], v[26:27], v[200:201]
	v_pk_mul_f32 v[202:203], v[20:21], v[202:203]
	v_pk_mul_f32 v[204:205], v[22:23], v[204:205]
	v_cvt_pk_bf16_f32 v218, v198, v199
	v_cvt_pk_bf16_f32 v219, v200, v201
	v_cvt_pk_bf16_f32 v220, v202, v203
	v_cvt_pk_bf16_f32 v221, v204, v205
	global_store_dwordx4 v187, v[218:221], s[34:35] offset:64
	v_add_u32_e32 v187, 0x58000, v186
	v_pk_mul_f32 v[190:191], v[16:17], s[38:39]
	v_pk_mul_f32 v[192:193], v[18:19], s[38:39]
	v_pk_mul_f32 v[194:195], v[12:13], s[38:39]
	v_pk_mul_f32 v[196:197], v[14:15], s[38:39]
	v_pk_mul_f32 v[190:191], v[16:17], v[190:191]
	v_pk_mul_f32 v[192:193], v[18:19], v[192:193]
	v_pk_mul_f32 v[194:195], v[12:13], v[194:195]
	v_pk_mul_f32 v[196:197], v[14:15], v[196:197]
	v_pk_fma_f32 v[190:191], v[16:17], v[190:191], v[16:17]
	v_pk_fma_f32 v[192:193], v[18:19], v[192:193], v[18:19]
	v_pk_fma_f32 v[194:195], v[12:13], v[194:195], v[12:13]
	v_pk_fma_f32 v[196:197], v[14:15], v[196:197], v[14:15]
	v_pk_mul_f32 v[190:191], v[190:191], s[40:41]
	v_pk_mul_f32 v[192:193], v[192:193], s[40:41]
	v_pk_mul_f32 v[194:195], v[194:195], s[40:41]
	v_pk_mul_f32 v[196:197], v[196:197], s[40:41]
	v_exp_f32_e32 v190, v190
	v_exp_f32_e32 v191, v191
	v_exp_f32_e32 v192, v192
	v_exp_f32_e32 v193, v193
	v_exp_f32_e32 v194, v194
	v_exp_f32_e32 v195, v195
	v_exp_f32_e32 v196, v196
	v_exp_f32_e32 v197, v197
	v_pk_add_f32 v[190:191], v[190:191], s[42:43]
	v_pk_add_f32 v[192:193], v[192:193], s[42:43]
	v_pk_add_f32 v[194:195], v[194:195], s[42:43]
	v_pk_add_f32 v[196:197], v[196:197], s[42:43]
	v_rcp_f32_e32 v190, v190
; __device__ __forceinline__ float fast_rcp(float x) { return __builtin_amdgcn_rcpf(x); }
; __device__ __forceinline__ float fast_exp2(float x) { return __builtin_amdgcn_exp2f(x); }
; __device__ __forceinline__ float sigmoid_f(float x) { return fast_rcp(1.0f + fast_exp2(-1.4426950409f * x)); }
; __device__ __forceinline__ float gelu_tanh(float x) { const float t = x + 0.044715f * x * x * x; return x * fast_rcp(1.0f + fast_exp2(-2.3022081981f * t)); }
; __device__ __forceinline__ f32x4 gelu4(f32x4 v) { return (f32x4){gelu_tanh(v[0]), gelu_tanh(v[1]), gelu_tanh(v[2]), gelu_tanh(v[3])}; }
; __device__ __forceinline__ f32x4 sigm4(f32x4 v) { return (f32x4){sigmoid_f(v[0]), sigmoid_f(v[1]), sigmoid_f(v[2]), sigmoid_f(v[3])}; }
;     __device__ __forceinline__ void operator()(f32x4 (&acc)[2][2][4][2], const Unit& u, int wr, int wc, int fr, int fq) const {
;     ...
;                         if (mode == 3) { u32x2 w; w.x = gate_q4(sigm4(v0)); w.y = gate_q4(sigm4(v1)); *(u32x2*)((unsigned char*)Gt + (size_t)row * 4096 + col0 + bj * 32) = w; continue; }
;                         if (mode == 0) { v0 = gelu4(v0); v1 = gelu4(v1); }
	v_rcp_f32_e32 v191, v191
	v_rcp_f32_e32 v192, v192
	v_rcp_f32_e32 v193, v193
	v_rcp_f32_e32 v194, v194
	v_rcp_f32_e32 v195, v195
	v_rcp_f32_e32 v196, v196
	v_rcp_f32_e32 v197, v197
	v_pk_mul_f32 v[190:191], v[16:17], v[190:191]
	v_pk_mul_f32 v[192:193], v[18:19], v[192:193]
	v_pk_mul_f32 v[194:195], v[12:13], v[194:195]
	v_pk_mul_f32 v[196:197], v[14:15], v[196:197]
	v_cvt_pk_bf16_f32 v224, v190, v191
	v_cvt_pk_bf16_f32 v225, v192, v193
	v_cvt_pk_bf16_f32 v226, v194, v195
	v_cvt_pk_bf16_f32 v227, v196, v197
	global_store_dwordx4 v187, v[224:227], s[34:35]
	v_pk_mul_f32 v[198:199], v[8:9], s[38:39]
	v_pk_mul_f32 v[200:201], v[10:11], s[38:39]
	v_pk_mul_f32 v[202:203], v[4:5], s[38:39]
	v_pk_mul_f32 v[204:205], v[6:7], s[38:39]
	v_pk_mul_f32 v[198:199], v[8:9], v[198:199]
	v_pk_mul_f32 v[200:201], v[10:11], v[200:201]
	v_pk_mul_f32 v[202:203], v[4:5], v[202:203]
	v_pk_mul_f32 v[204:205], v[6:7], v[204:205]
	v_pk_fma_f32 v[198:199], v[8:9], v[198:199], v[8:9]
	v_pk_fma_f32 v[200:201], v[10:11], v[200:201], v[10:11]
	v_pk_fma_f32 v[202:203], v[4:5], v[202:203], v[4:5]
	v_pk_fma_f32 v[204:205], v[6:7], v[204:205], v[6:7]
	v_pk_mul_f32 v[198:199], v[198:199], s[40:41]
	v_pk_mul_f32 v[200:201], v[200:201], s[40:41]
	v_pk_mul_f32 v[202:203], v[202:203], s[40:41]
	v_pk_mul_f32 v[204:205], v[204:205], s[40:41]
	v_exp_f32_e32 v198, v198
	v_exp_f32_e32 v199, v199
	v_exp_f32_e32 v200, v200
	v_exp_f32_e32 v201, v201
	v_exp_f32_e32 v202, v202
	v_exp_f32_e32 v203, v203
	v_exp_f32_e32 v204, v204
	v_exp_f32_e32 v205, v205
	v_pk_add_f32 v[198:199], v[198:199], s[42:43]
	v_pk_add_f32 v[200:201], v[200:201], s[42:43]
	v_pk_add_f32 v[202:203], v[202:203], s[42:43]
	v_pk_add_f32 v[204:205], v[204:205], s[42:43]
	v_rcp_f32_e32 v198, v198
	v_rcp_f32_e32 v199, v199
	v_rcp_f32_e32 v200, v200
	v_rcp_f32_e32 v201, v201
	v_rcp_f32_e32 v202, v202
	v_rcp_f32_e32 v203, v203
	v_rcp_f32_e32 v204, v204
	v_rcp_f32_e32 v205, v205
	v_pk_mul_f32 v[198:199], v[8:9], v[198:199]
	v_pk_mul_f32 v[200:201], v[10:11], v[200:201]
	v_pk_mul_f32 v[202:203], v[4:5], v[202:203]
	v_pk_mul_f32 v[204:205], v[6:7], v[204:205]
	v_cvt_pk_bf16_f32 v228, v198, v199
	v_cvt_pk_bf16_f32 v229, v200, v201
	v_cvt_pk_bf16_f32 v230, v202, v203
	v_cvt_pk_bf16_f32 v231, v204, v205
	global_store_dwordx4 v187, v[228:231], s[34:35] offset:64
	s_branch .Lp1e_done
.Lp1e_gates:
	s_mov_b32 s38, 0xbfb8aa3b
	s_mov_b32 s39, 0xbfb8aa3b
	s_mov_b32 s40, 0x437f0000
	s_mov_b32 s41, 0x437f0000
	v_lshl_add_u32 v186, v184, 12, v185
	v_pk_mul_f32 v[190:191], v[128:129], s[38:39]
	v_pk_mul_f32 v[192:193], v[130:131], s[38:39]
	v_pk_mul_f32 v[194:195], v[124:125], s[38:39]
	v_pk_mul_f32 v[196:197], v[126:127], s[38:39]
	v_exp_f32_e32 v190, v190
	v_exp_f32_e32 v191, v191
	v_exp_f32_e32 v192, v192
	v_exp_f32_e32 v193, v193
	v_exp_f32_e32 v194, v194
	v_exp_f32_e32 v195, v195
	v_exp_f32_e32 v196, v196
	v_exp_f32_e32 v197, v197
	v_pk_add_f32 v[190:191], v[190:191], s[42:43]
	v_pk_add_f32 v[192:193], v[192:193], s[42:43]
	v_pk_add_f32 v[194:195], v[194:195], s[42:43]
	v_pk_add_f32 v[196:197], v[196:197], s[42:43]
	v_rcp_f32_e32 v190, v190
	v_rcp_f32_e32 v191, v191
	v_rcp_f32_e32 v192, v192
	v_rcp_f32_e32 v193, v193
	v_rcp_f32_e32 v194, v194
	v_rcp_f32_e32 v195, v195
	v_rcp_f32_e32 v196, v196
	v_rcp_f32_e32 v197, v197
	v_pk_fma_f32 v[190:191], v[190:191], s[40:41], 0.5 op_sel_hi:[1,1,0]
	v_pk_fma_f32 v[192:193], v[192:193], s[40:41], 0.5 op_sel_hi:[1,1,0]
	v_pk_fma_f32 v[194:195], v[194:195], s[40:41], 0.5 op_sel_hi:[1,1,0]
	v_pk_fma_f32 v[196:197], v[196:197], s[40:41], 0.5 op_sel_hi:[1,1,0]
	v_cvt_u32_f32_e32 v190, v190
	v_cvt_u32_f32_e32 v191, v191
	v_cvt_u32_f32_e32 v192, v192
	v_cvt_u32_f32_e32 v193, v193
	v_cvt_u32_f32_e32 v194, v194
	v_cvt_u32_f32_e32 v195, v195
	v_cvt_u32_f32_e32 v196, v196
	v_cvt_u32_f32_e32 v197, v197
	v_lshl_or_b32 v190, v191, 8, v190
	v_lshl_or_b32 v192, v193, 8, v192
	v_lshl_or_b32 v194, v195, 8, v194
	v_lshl_or_b32 v196, v197, 8, v196
	v_lshl_or_b32 v206, v192, 16, v190
	v_lshl_or_b32 v207, v196, 16, v194
	global_store_dwordx2 v186, v[206:207], s[54:55]
	v_pk_mul_f32 v[198:199], v[120:121], s[38:39]
	v_pk_mul_f32 v[200:201], v[122:123], s[38:39]
	v_pk_mul_f32 v[202:203], v[116:117], s[38:39]
	v_pk_mul_f32 v[204:205], v[118:119], s[38:39]
	v_exp_f32_e32 v198, v198
	v_exp_f32_e32 v199, v199
	v_exp_f32_e32 v200, v200
	v_exp_f32_e32 v201, v201
	v_exp_f32_e32 v202, v202
	v_exp_f32_e32 v203, v203
	v_exp_f32_e32 v204, v204
	v_exp_f32_e32 v205, v205
	v_pk_add_f32 v[198:199], v[198:199], s[42:43]
	v_pk_add_f32 v[200:201], v[200:201], s[42:43]
	v_pk_add_f32 v[202:203], v[202:203], s[42:43]
	v_pk_add_f32 v[204:205], v[204:205], s[42:43]
	v_rcp_f32_e32 v198, v198
	v_rcp_f32_e32 v199, v199
	v_rcp_f32_e32 v200, v200
	v_rcp_f32_e32 v201, v201
	v_rcp_f32_e32 v202, v202
	v_rcp_f32_e32 v203, v203
	v_rcp_f32_e32 v204, v204
	v_rcp_f32_e32 v205, v205
	v_pk_fma_f32 v[198:199], v[198:199], s[40:41], 0.5 op_sel_hi:[1,1,0]
	v_pk_fma_f32 v[200:201], v[200:201], s[40:41], 0.5 op_sel_hi:[1,1,0]
	v_pk_fma_f32 v[202:203], v[202:203], s[40:41], 0.5 op_sel_hi:[1,1,0]
	v_pk_fma_f32 v[204:205], v[204:205], s[40:41], 0.5 op_sel_hi:[1,1,0]
	v_cvt_u32_f32_e32 v198, v198
	v_cvt_u32_f32_e32 v199, v199
	v_cvt_u32_f32_e32 v200, v200
	v_cvt_u32_f32_e32 v201, v201
	v_cvt_u32_f32_e32 v202, v202
	v_cvt_u32_f32_e32 v203, v203
	v_cvt_u32_f32_e32 v204, v204
	v_cvt_u32_f32_e32 v205, v205
	v_lshl_or_b32 v198, v199, 8, v198
	v_lshl_or_b32 v200, v201, 8, v200
	v_lshl_or_b32 v202, v203, 8, v202
	v_lshl_or_b32 v204, v205, 8, v204
	v_lshl_or_b32 v218, v200, 16, v198
	v_lshl_or_b32 v219, v204, 16, v202
	global_store_dwordx2 v186, v[218:219], s[54:55] offset:32
; __device__ __forceinline__ float fast_rcp(float x) { return __builtin_amdgcn_rcpf(x); }
; __device__ __forceinline__ float fast_exp2(float x) { return __builtin_amdgcn_exp2f(x); }
; __device__ __forceinline__ float sigmoid_f(float x) { return fast_rcp(1.0f + fast_exp2(-1.4426950409f * x)); }
; __device__ __forceinline__ float gelu_tanh(float x) { const float t = x + 0.044715f * x * x * x; return x * fast_rcp(1.0f + fast_exp2(-2.3022081981f * t)); }
; __device__ __forceinline__ f32x4 gelu4(f32x4 v) { return (f32x4){gelu_tanh(v[0]), gelu_tanh(v[1]), gelu_tanh(v[2]), gelu_tanh(v[3])}; }
; __device__ __forceinline__ f32x4 sigm4(f32x4 v) { return (f32x4){sigmoid_f(v[0]), sigmoid_f(v[1]), sigmoid_f(v[2]), sigmoid_f(v[3])}; }
;     __device__ __forceinline__ void operator()(f32x4 (&acc)[2][2][4][2], const Unit& u, int wr, int wc, int fr, int fq) const {
;     ...
;                         if (mode == 3) { u32x2 w; w.x = gate_q4(sigm4(v0)); w.y = gate_q4(sigm4(v1)); *(u32x2*)((unsigned char*)Gt + (size_t)row * 4096 + col0 + bj * 32) = w; continue; }
	v_add_u32_e32 v187, 0x10000, v186
	v_pk_mul_f32 v[190:191], v[112:113], s[38:39]
	v_pk_mul_f32 v[192:193], v[114:115], s[38:39]
	v_pk_mul_f32 v[194:195], v[108:109], s[38:39]
	v_pk_mul_f32 v[196:197], v[110:111], s[38:39]
	v_exp_f32_e32 v190, v190
	v_exp_f32_e32 v191, v191
	v_exp_f32_e32 v192, v192
	v_exp_f32_e32 v193, v193
	v_exp_f32_e32 v194, v194
	v_exp_f32_e32 v195, v195
	v_exp_f32_e32 v196, v196
	v_exp_f32_e32 v197, v197
	v_pk_add_f32 v[190:191], v[190:191], s[42:43]
	v_pk_add_f32 v[192:193], v[192:193], s[42:43]
	v_pk_add_f32 v[194:195], v[194:195], s[42:43]
	v_pk_add_f32 v[196:197], v[196:197], s[42:43]
	v_rcp_f32_e32 v190, v190
	v_rcp_f32_e32 v191, v191
	v_rcp_f32_e32 v192, v192
	v_rcp_f32_e32 v193, v193
	v_rcp_f32_e32 v194, v194
	v_rcp_f32_e32 v195, v195
	v_rcp_f32_e32 v196, v196
	v_rcp_f32_e32 v197, v197
	v_pk_fma_f32 v[190:191], v[190:191], s[40:41], 0.5 op_sel_hi:[1,1,0]
	v_pk_fma_f32 v[192:193], v[192:193], s[40:41], 0.5 op_sel_hi:[1,1,0]
	v_pk_fma_f32 v[194:195], v[194:195], s[40:41], 0.5 op_sel_hi:[1,1,0]
	v_pk_fma_f32 v[196:197], v[196:197], s[40:41], 0.5 op_sel_hi:[1,1,0]
	v_cvt_u32_f32_e32 v190, v190
	v_cvt_u32_f32_e32 v191, v191
	v_cvt_u32_f32_e32 v192, v192
	v_cvt_u32_f32_e32 v193, v193
	v_cvt_u32_f32_e32 v194, v194
	v_cvt_u32_f32_e32 v195, v195
	v_cvt_u32_f32_e32 v196, v196
	v_cvt_u32_f32_e32 v197, v197
	v_lshl_or_b32 v190, v191, 8, v190
	v_lshl_or_b32 v192, v193, 8, v192
	v_lshl_or_b32 v194, v195, 8, v194
	v_lshl_or_b32 v196, v197, 8, v196
	v_lshl_or_b32 v224, v192, 16, v190
	v_lshl_or_b32 v225, v196, 16, v194
	global_store_dwordx2 v187, v[224:225], s[54:55]
	v_pk_mul_f32 v[198:199], v[104:105], s[38:39]
	v_pk_mul_f32 v[200:201], v[106:107], s[38:39]
	v_pk_mul_f32 v[202:203], v[100:101], s[38:39]
	v_pk_mul_f32 v[204:205], v[102:103], s[38:39]
	v_exp_f32_e32 v198, v198
	v_exp_f32_e32 v199, v199
	v_exp_f32_e32 v200, v200
	v_exp_f32_e32 v201, v201
	v_exp_f32_e32 v202, v202
	v_exp_f32_e32 v203, v203
	v_exp_f32_e32 v204, v204
	v_exp_f32_e32 v205, v205
	v_pk_add_f32 v[198:199], v[198:199], s[42:43]
	v_pk_add_f32 v[200:201], v[200:201], s[42:43]
	v_pk_add_f32 v[202:203], v[202:203], s[42:43]
	v_pk_add_f32 v[204:205], v[204:205], s[42:43]
	v_rcp_f32_e32 v198, v198
	v_rcp_f32_e32 v199, v199
	v_rcp_f32_e32 v200, v200
	v_rcp_f32_e32 v201, v201
	v_rcp_f32_e32 v202, v202
	v_rcp_f32_e32 v203, v203
	v_rcp_f32_e32 v204, v204
	v_rcp_f32_e32 v205, v205
	v_pk_fma_f32 v[198:199], v[198:199], s[40:41], 0.5 op_sel_hi:[1,1,0]
	v_pk_fma_f32 v[200:201], v[200:201], s[40:41], 0.5 op_sel_hi:[1,1,0]
	v_pk_fma_f32 v[202:203], v[202:203], s[40:41], 0.5 op_sel_hi:[1,1,0]
	v_pk_fma_f32 v[204:205], v[204:205], s[40:41], 0.5 op_sel_hi:[1,1,0]
	v_cvt_u32_f32_e32 v198, v198
	v_cvt_u32_f32_e32 v199, v199
	v_cvt_u32_f32_e32 v200, v200
	v_cvt_u32_f32_e32 v201, v201
	v_cvt_u32_f32_e32 v202, v202
	v_cvt_u32_f32_e32 v203, v203
	v_cvt_u32_f32_e32 v204, v204
	v_cvt_u32_f32_e32 v205, v205
	v_lshl_or_b32 v198, v199, 8, v198
	v_lshl_or_b32 v200, v201, 8, v200
	v_lshl_or_b32 v202, v203, 8, v202
	v_lshl_or_b32 v204, v205, 8, v204
	v_lshl_or_b32 v228, v200, 16, v198
	v_lshl_or_b32 v229, v204, 16, v202
	global_store_dwordx2 v187, v[228:229], s[54:55] offset:32
	v_add_u32_e32 v187, 0x20000, v186
	v_pk_mul_f32 v[190:191], v[96:97], s[38:39]
	v_pk_mul_f32 v[192:193], v[98:99], s[38:39]
	v_pk_mul_f32 v[194:195], v[92:93], s[38:39]
	v_pk_mul_f32 v[196:197], v[94:95], s[38:39]
	v_exp_f32_e32 v190, v190
	v_exp_f32_e32 v191, v191
	v_exp_f32_e32 v192, v192
	v_exp_f32_e32 v193, v193
	v_exp_f32_e32 v194, v194
	v_exp_f32_e32 v195, v195
	v_exp_f32_e32 v196, v196
	v_exp_f32_e32 v197, v197
	v_pk_add_f32 v[190:191], v[190:191], s[42:43]
	v_pk_add_f32 v[192:193], v[192:193], s[42:43]
	v_pk_add_f32 v[194:195], v[194:195], s[42:43]
	v_pk_add_f32 v[196:197], v[196:197], s[42:43]
	v_rcp_f32_e32 v190, v190
	v_rcp_f32_e32 v191, v191
	v_rcp_f32_e32 v192, v192
	v_rcp_f32_e32 v193, v193
	v_rcp_f32_e32 v194, v194
	v_rcp_f32_e32 v195, v195
	v_rcp_f32_e32 v196, v196
	v_rcp_f32_e32 v197, v197
	v_pk_fma_f32 v[190:191], v[190:191], s[40:41], 0.5 op_sel_hi:[1,1,0]
	v_pk_fma_f32 v[192:193], v[192:193], s[40:41], 0.5 op_sel_hi:[1,1,0]
	v_pk_fma_f32 v[194:195], v[194:195], s[40:41], 0.5 op_sel_hi:[1,1,0]
	v_pk_fma_f32 v[196:197], v[196:197], s[40:41], 0.5 op_sel_hi:[1,1,0]
	v_cvt_u32_f32_e32 v190, v190
	v_cvt_u32_f32_e32 v191, v191
	v_cvt_u32_f32_e32 v192, v192
	v_cvt_u32_f32_e32 v193, v193
	v_cvt_u32_f32_e32 v194, v194
	v_cvt_u32_f32_e32 v195, v195
	v_cvt_u32_f32_e32 v196, v196
	v_cvt_u32_f32_e32 v197, v197
	v_lshl_or_b32 v190, v191, 8, v190
	v_lshl_or_b32 v192, v193, 8, v192
	v_lshl_or_b32 v194, v195, 8, v194
	v_lshl_or_b32 v196, v197, 8, v196
	v_lshl_or_b32 v206, v192, 16, v190
	v_lshl_or_b32 v207, v196, 16, v194
	global_store_dwordx2 v187, v[206:207], s[54:55]
	v_pk_mul_f32 v[198:199], v[88:89], s[38:39]
	v_pk_mul_f32 v[200:201], v[90:91], s[38:39]
	v_pk_mul_f32 v[202:203], v[84:85], s[38:39]
	v_pk_mul_f32 v[204:205], v[86:87], s[38:39]
	v_exp_f32_e32 v198, v198
	v_exp_f32_e32 v199, v199
	v_exp_f32_e32 v200, v200
	v_exp_f32_e32 v201, v201
	v_exp_f32_e32 v202, v202
	v_exp_f32_e32 v203, v203
	v_exp_f32_e32 v204, v204
	v_exp_f32_e32 v205, v205
	v_pk_add_f32 v[198:199], v[198:199], s[42:43]
	v_pk_add_f32 v[200:201], v[200:201], s[42:43]
	v_pk_add_f32 v[202:203], v[202:203], s[42:43]
	v_pk_add_f32 v[204:205], v[204:205], s[42:43]
	v_rcp_f32_e32 v198, v198
	v_rcp_f32_e32 v199, v199
	v_rcp_f32_e32 v200, v200
	v_rcp_f32_e32 v201, v201
	v_rcp_f32_e32 v202, v202
	v_rcp_f32_e32 v203, v203
	v_rcp_f32_e32 v204, v204
	v_rcp_f32_e32 v205, v205
	v_pk_fma_f32 v[198:199], v[198:199], s[40:41], 0.5 op_sel_hi:[1,1,0]
; __device__ __forceinline__ float fast_rcp(float x) { return __builtin_amdgcn_rcpf(x); }
; __device__ __forceinline__ float fast_exp2(float x) { return __builtin_amdgcn_exp2f(x); }
; __device__ __forceinline__ float sigmoid_f(float x) { return fast_rcp(1.0f + fast_exp2(-1.4426950409f * x)); }
; __device__ __forceinline__ float gelu_tanh(float x) { const float t = x + 0.044715f * x * x * x; return x * fast_rcp(1.0f + fast_exp2(-2.3022081981f * t)); }
; __device__ __forceinline__ f32x4 gelu4(f32x4 v) { return (f32x4){gelu_tanh(v[0]), gelu_tanh(v[1]), gelu_tanh(v[2]), gelu_tanh(v[3])}; }
; __device__ __forceinline__ f32x4 sigm4(f32x4 v) { return (f32x4){sigmoid_f(v[0]), sigmoid_f(v[1]), sigmoid_f(v[2]), sigmoid_f(v[3])}; }
;     __device__ __forceinline__ void operator()(f32x4 (&acc)[2][2][4][2], const Unit& u, int wr, int wc, int fr, int fq) const {
;     ...
;                         if (mode == 3) { u32x2 w; w.x = gate_q4(sigm4(v0)); w.y = gate_q4(sigm4(v1)); *(u32x2*)((unsigned char*)Gt + (size_t)row * 4096 + col0 + bj * 32) = w; continue; }
	v_pk_fma_f32 v[200:201], v[200:201], s[40:41], 0.5 op_sel_hi:[1,1,0]
	v_pk_fma_f32 v[202:203], v[202:203], s[40:41], 0.5 op_sel_hi:[1,1,0]
	v_pk_fma_f32 v[204:205], v[204:205], s[40:41], 0.5 op_sel_hi:[1,1,0]
	v_cvt_u32_f32_e32 v198, v198
	v_cvt_u32_f32_e32 v199, v199
	v_cvt_u32_f32_e32 v200, v200
	v_cvt_u32_f32_e32 v201, v201
	v_cvt_u32_f32_e32 v202, v202
	v_cvt_u32_f32_e32 v203, v203
	v_cvt_u32_f32_e32 v204, v204
	v_cvt_u32_f32_e32 v205, v205
	v_lshl_or_b32 v198, v199, 8, v198
	v_lshl_or_b32 v200, v201, 8, v200
	v_lshl_or_b32 v202, v203, 8, v202
	v_lshl_or_b32 v204, v205, 8, v204
	v_lshl_or_b32 v218, v200, 16, v198
	v_lshl_or_b32 v219, v204, 16, v202
	global_store_dwordx2 v187, v[218:219], s[54:55] offset:32
	v_add_u32_e32 v187, 0x30000, v186
	v_pk_mul_f32 v[190:191], v[80:81], s[38:39]
	v_pk_mul_f32 v[192:193], v[82:83], s[38:39]
	v_pk_mul_f32 v[194:195], v[76:77], s[38:39]
	v_pk_mul_f32 v[196:197], v[78:79], s[38:39]
	v_exp_f32_e32 v190, v190
	v_exp_f32_e32 v191, v191
	v_exp_f32_e32 v192, v192
	v_exp_f32_e32 v193, v193
	v_exp_f32_e32 v194, v194
	v_exp_f32_e32 v195, v195
	v_exp_f32_e32 v196, v196
	v_exp_f32_e32 v197, v197
	v_pk_add_f32 v[190:191], v[190:191], s[42:43]
	v_pk_add_f32 v[192:193], v[192:193], s[42:43]
	v_pk_add_f32 v[194:195], v[194:195], s[42:43]
	v_pk_add_f32 v[196:197], v[196:197], s[42:43]
	v_rcp_f32_e32 v190, v190
	v_rcp_f32_e32 v191, v191
	v_rcp_f32_e32 v192, v192
	v_rcp_f32_e32 v193, v193
	v_rcp_f32_e32 v194, v194
	v_rcp_f32_e32 v195, v195
	v_rcp_f32_e32 v196, v196
	v_rcp_f32_e32 v197, v197
	v_pk_fma_f32 v[190:191], v[190:191], s[40:41], 0.5 op_sel_hi:[1,1,0]
	v_pk_fma_f32 v[192:193], v[192:193], s[40:41], 0.5 op_sel_hi:[1,1,0]
	v_pk_fma_f32 v[194:195], v[194:195], s[40:41], 0.5 op_sel_hi:[1,1,0]
	v_pk_fma_f32 v[196:197], v[196:197], s[40:41], 0.5 op_sel_hi:[1,1,0]
	v_cvt_u32_f32_e32 v190, v190
	v_cvt_u32_f32_e32 v191, v191
	v_cvt_u32_f32_e32 v192, v192
	v_cvt_u32_f32_e32 v193, v193
	v_cvt_u32_f32_e32 v194, v194
	v_cvt_u32_f32_e32 v195, v195
	v_cvt_u32_f32_e32 v196, v196
	v_cvt_u32_f32_e32 v197, v197
	v_lshl_or_b32 v190, v191, 8, v190
	v_lshl_or_b32 v192, v193, 8, v192
	v_lshl_or_b32 v194, v195, 8, v194
	v_lshl_or_b32 v196, v197, 8, v196
	v_lshl_or_b32 v224, v192, 16, v190
	v_lshl_or_b32 v225, v196, 16, v194
	global_store_dwordx2 v187, v[224:225], s[54:55]
	v_pk_mul_f32 v[198:199], v[72:73], s[38:39]
	v_pk_mul_f32 v[200:201], v[74:75], s[38:39]
	v_pk_mul_f32 v[202:203], v[68:69], s[38:39]
	v_pk_mul_f32 v[204:205], v[70:71], s[38:39]
	v_exp_f32_e32 v198, v198
	v_exp_f32_e32 v199, v199
	v_exp_f32_e32 v200, v200
	v_exp_f32_e32 v201, v201
	v_exp_f32_e32 v202, v202
	v_exp_f32_e32 v203, v203
	v_exp_f32_e32 v204, v204
	v_exp_f32_e32 v205, v205
	v_pk_add_f32 v[198:199], v[198:199], s[42:43]
	v_pk_add_f32 v[200:201], v[200:201], s[42:43]
	v_pk_add_f32 v[202:203], v[202:203], s[42:43]
	v_pk_add_f32 v[204:205], v[204:205], s[42:43]
	v_rcp_f32_e32 v198, v198
	v_rcp_f32_e32 v199, v199
	v_rcp_f32_e32 v200, v200
	v_rcp_f32_e32 v201, v201
	v_rcp_f32_e32 v202, v202
	v_rcp_f32_e32 v203, v203
	v_rcp_f32_e32 v204, v204
	v_rcp_f32_e32 v205, v205
	v_pk_fma_f32 v[198:199], v[198:199], s[40:41], 0.5 op_sel_hi:[1,1,0]
	v_pk_fma_f32 v[200:201], v[200:201], s[40:41], 0.5 op_sel_hi:[1,1,0]
	v_pk_fma_f32 v[202:203], v[202:203], s[40:41], 0.5 op_sel_hi:[1,1,0]
	v_pk_fma_f32 v[204:205], v[204:205], s[40:41], 0.5 op_sel_hi:[1,1,0]
	v_cvt_u32_f32_e32 v198, v198
	v_cvt_u32_f32_e32 v199, v199
	v_cvt_u32_f32_e32 v200, v200
	v_cvt_u32_f32_e32 v201, v201
	v_cvt_u32_f32_e32 v202, v202
	v_cvt_u32_f32_e32 v203, v203
	v_cvt_u32_f32_e32 v204, v204
	v_cvt_u32_f32_e32 v205, v205
	v_lshl_or_b32 v198, v199, 8, v198
	v_lshl_or_b32 v200, v201, 8, v200
	v_lshl_or_b32 v202, v203, 8, v202
	v_lshl_or_b32 v204, v205, 8, v204
	v_lshl_or_b32 v228, v200, 16, v198
	v_lshl_or_b32 v229, v204, 16, v202
	global_store_dwordx2 v187, v[228:229], s[54:55] offset:32
	v_add_u32_e32 v187, 0x80000, v186
	v_pk_mul_f32 v[190:191], v[64:65], s[38:39]
	v_pk_mul_f32 v[192:193], v[66:67], s[38:39]
	v_pk_mul_f32 v[194:195], v[60:61], s[38:39]
	v_pk_mul_f32 v[196:197], v[62:63], s[38:39]
	v_exp_f32_e32 v190, v190
	v_exp_f32_e32 v191, v191
	v_exp_f32_e32 v192, v192
	v_exp_f32_e32 v193, v193
	v_exp_f32_e32 v194, v194
	v_exp_f32_e32 v195, v195
	v_exp_f32_e32 v196, v196
	v_exp_f32_e32 v197, v197
	v_pk_add_f32 v[190:191], v[190:191], s[42:43]
	v_pk_add_f32 v[192:193], v[192:193], s[42:43]
	v_pk_add_f32 v[194:195], v[194:195], s[42:43]
	v_pk_add_f32 v[196:197], v[196:197], s[42:43]
	v_rcp_f32_e32 v190, v190
	v_rcp_f32_e32 v191, v191
	v_rcp_f32_e32 v192, v192
	v_rcp_f32_e32 v193, v193
	v_rcp_f32_e32 v194, v194
	v_rcp_f32_e32 v195, v195
	v_rcp_f32_e32 v196, v196
	v_rcp_f32_e32 v197, v197
	v_pk_fma_f32 v[190:191], v[190:191], s[40:41], 0.5 op_sel_hi:[1,1,0]
	v_pk_fma_f32 v[192:193], v[192:193], s[40:41], 0.5 op_sel_hi:[1,1,0]
	v_pk_fma_f32 v[194:195], v[194:195], s[40:41], 0.5 op_sel_hi:[1,1,0]
	v_pk_fma_f32 v[196:197], v[196:197], s[40:41], 0.5 op_sel_hi:[1,1,0]
	v_cvt_u32_f32_e32 v190, v190
	v_cvt_u32_f32_e32 v191, v191
	v_cvt_u32_f32_e32 v192, v192
	v_cvt_u32_f32_e32 v193, v193
	v_cvt_u32_f32_e32 v194, v194
	v_cvt_u32_f32_e32 v195, v195
	v_cvt_u32_f32_e32 v196, v196
	v_cvt_u32_f32_e32 v197, v197
	v_lshl_or_b32 v190, v191, 8, v190
	v_lshl_or_b32 v192, v193, 8, v192
	v_lshl_or_b32 v194, v195, 8, v194
	v_lshl_or_b32 v196, v197, 8, v196
	v_lshl_or_b32 v206, v192, 16, v190
	v_lshl_or_b32 v207, v196, 16, v194
	global_store_dwordx2 v187, v[206:207], s[54:55]
	v_pk_mul_f32 v[198:199], v[56:57], s[38:39]
	v_pk_mul_f32 v[200:201], v[58:59], s[38:39]
	v_pk_mul_f32 v[202:203], v[52:53], s[38:39]
; __device__ __forceinline__ float fast_rcp(float x) { return __builtin_amdgcn_rcpf(x); }
; __device__ __forceinline__ float fast_exp2(float x) { return __builtin_amdgcn_exp2f(x); }
; __device__ __forceinline__ float sigmoid_f(float x) { return fast_rcp(1.0f + fast_exp2(-1.4426950409f * x)); }
; __device__ __forceinline__ float gelu_tanh(float x) { const float t = x + 0.044715f * x * x * x; return x * fast_rcp(1.0f + fast_exp2(-2.3022081981f * t)); }
; __device__ __forceinline__ f32x4 gelu4(f32x4 v) { return (f32x4){gelu_tanh(v[0]), gelu_tanh(v[1]), gelu_tanh(v[2]), gelu_tanh(v[3])}; }
; __device__ __forceinline__ f32x4 sigm4(f32x4 v) { return (f32x4){sigmoid_f(v[0]), sigmoid_f(v[1]), sigmoid_f(v[2]), sigmoid_f(v[3])}; }
;     __device__ __forceinline__ void operator()(f32x4 (&acc)[2][2][4][2], const Unit& u, int wr, int wc, int fr, int fq) const {
;     ...
;                         if (mode == 3) { u32x2 w; w.x = gate_q4(sigm4(v0)); w.y = gate_q4(sigm4(v1)); *(u32x2*)((unsigned char*)Gt + (size_t)row * 4096 + col0 + bj * 32) = w; continue; }
	v_pk_mul_f32 v[204:205], v[54:55], s[38:39]
	v_exp_f32_e32 v198, v198
	v_exp_f32_e32 v199, v199
	v_exp_f32_e32 v200, v200
	v_exp_f32_e32 v201, v201
	v_exp_f32_e32 v202, v202
	v_exp_f32_e32 v203, v203
	v_exp_f32_e32 v204, v204
	v_exp_f32_e32 v205, v205
	v_pk_add_f32 v[198:199], v[198:199], s[42:43]
	v_pk_add_f32 v[200:201], v[200:201], s[42:43]
	v_pk_add_f32 v[202:203], v[202:203], s[42:43]
	v_pk_add_f32 v[204:205], v[204:205], s[42:43]
	v_rcp_f32_e32 v198, v198
	v_rcp_f32_e32 v199, v199
	v_rcp_f32_e32 v200, v200
	v_rcp_f32_e32 v201, v201
	v_rcp_f32_e32 v202, v202
	v_rcp_f32_e32 v203, v203
	v_rcp_f32_e32 v204, v204
	v_rcp_f32_e32 v205, v205
	v_pk_fma_f32 v[198:199], v[198:199], s[40:41], 0.5 op_sel_hi:[1,1,0]
	v_pk_fma_f32 v[200:201], v[200:201], s[40:41], 0.5 op_sel_hi:[1,1,0]
	v_pk_fma_f32 v[202:203], v[202:203], s[40:41], 0.5 op_sel_hi:[1,1,0]
	v_pk_fma_f32 v[204:205], v[204:205], s[40:41], 0.5 op_sel_hi:[1,1,0]
	v_cvt_u32_f32_e32 v198, v198
	v_cvt_u32_f32_e32 v199, v199
	v_cvt_u32_f32_e32 v200, v200
	v_cvt_u32_f32_e32 v201, v201
	v_cvt_u32_f32_e32 v202, v202
	v_cvt_u32_f32_e32 v203, v203
	v_cvt_u32_f32_e32 v204, v204
	v_cvt_u32_f32_e32 v205, v205
	v_lshl_or_b32 v198, v199, 8, v198
	v_lshl_or_b32 v200, v201, 8, v200
	v_lshl_or_b32 v202, v203, 8, v202
	v_lshl_or_b32 v204, v205, 8, v204
	v_lshl_or_b32 v218, v200, 16, v198
	v_lshl_or_b32 v219, v204, 16, v202
	global_store_dwordx2 v187, v[218:219], s[54:55] offset:32
	v_add_u32_e32 v187, 0x90000, v186
	v_pk_mul_f32 v[190:191], v[48:49], s[38:39]
	v_pk_mul_f32 v[192:193], v[50:51], s[38:39]
	v_pk_mul_f32 v[194:195], v[44:45], s[38:39]
	v_pk_mul_f32 v[196:197], v[46:47], s[38:39]
	v_exp_f32_e32 v190, v190
	v_exp_f32_e32 v191, v191
	v_exp_f32_e32 v192, v192
	v_exp_f32_e32 v193, v193
	v_exp_f32_e32 v194, v194
	v_exp_f32_e32 v195, v195
	v_exp_f32_e32 v196, v196
	v_exp_f32_e32 v197, v197
	v_pk_add_f32 v[190:191], v[190:191], s[42:43]
	v_pk_add_f32 v[192:193], v[192:193], s[42:43]
	v_pk_add_f32 v[194:195], v[194:195], s[42:43]
	v_pk_add_f32 v[196:197], v[196:197], s[42:43]
	v_rcp_f32_e32 v190, v190
	v_rcp_f32_e32 v191, v191
	v_rcp_f32_e32 v192, v192
	v_rcp_f32_e32 v193, v193
	v_rcp_f32_e32 v194, v194
	v_rcp_f32_e32 v195, v195
	v_rcp_f32_e32 v196, v196
	v_rcp_f32_e32 v197, v197
	v_pk_fma_f32 v[190:191], v[190:191], s[40:41], 0.5 op_sel_hi:[1,1,0]
	v_pk_fma_f32 v[192:193], v[192:193], s[40:41], 0.5 op_sel_hi:[1,1,0]
	v_pk_fma_f32 v[194:195], v[194:195], s[40:41], 0.5 op_sel_hi:[1,1,0]
	v_pk_fma_f32 v[196:197], v[196:197], s[40:41], 0.5 op_sel_hi:[1,1,0]
	v_cvt_u32_f32_e32 v190, v190
	v_cvt_u32_f32_e32 v191, v191
	v_cvt_u32_f32_e32 v192, v192
	v_cvt_u32_f32_e32 v193, v193
	v_cvt_u32_f32_e32 v194, v194
	v_cvt_u32_f32_e32 v195, v195
	v_cvt_u32_f32_e32 v196, v196
	v_cvt_u32_f32_e32 v197, v197
	v_lshl_or_b32 v190, v191, 8, v190
	v_lshl_or_b32 v192, v193, 8, v192
	v_lshl_or_b32 v194, v195, 8, v194
	v_lshl_or_b32 v196, v197, 8, v196
	v_lshl_or_b32 v224, v192, 16, v190
	v_lshl_or_b32 v225, v196, 16, v194
	global_store_dwordx2 v187, v[224:225], s[54:55]
	v_pk_mul_f32 v[198:199], v[40:41], s[38:39]
	v_pk_mul_f32 v[200:201], v[42:43], s[38:39]
	v_pk_mul_f32 v[202:203], v[36:37], s[38:39]
	v_pk_mul_f32 v[204:205], v[38:39], s[38:39]
	v_exp_f32_e32 v198, v198
	v_exp_f32_e32 v199, v199
	v_exp_f32_e32 v200, v200
	v_exp_f32_e32 v201, v201
	v_exp_f32_e32 v202, v202
	v_exp_f32_e32 v203, v203
	v_exp_f32_e32 v204, v204
	v_exp_f32_e32 v205, v205
	v_pk_add_f32 v[198:199], v[198:199], s[42:43]
	v_pk_add_f32 v[200:201], v[200:201], s[42:43]
	v_pk_add_f32 v[202:203], v[202:203], s[42:43]
	v_pk_add_f32 v[204:205], v[204:205], s[42:43]
	v_rcp_f32_e32 v198, v198
	v_rcp_f32_e32 v199, v199
	v_rcp_f32_e32 v200, v200
	v_rcp_f32_e32 v201, v201
	v_rcp_f32_e32 v202, v202
	v_rcp_f32_e32 v203, v203
	v_rcp_f32_e32 v204, v204
	v_rcp_f32_e32 v205, v205
	v_pk_fma_f32 v[198:199], v[198:199], s[40:41], 0.5 op_sel_hi:[1,1,0]
	v_pk_fma_f32 v[200:201], v[200:201], s[40:41], 0.5 op_sel_hi:[1,1,0]
	v_pk_fma_f32 v[202:203], v[202:203], s[40:41], 0.5 op_sel_hi:[1,1,0]
	v_pk_fma_f32 v[204:205], v[204:205], s[40:41], 0.5 op_sel_hi:[1,1,0]
	v_cvt_u32_f32_e32 v198, v198
	v_cvt_u32_f32_e32 v199, v199
	v_cvt_u32_f32_e32 v200, v200
	v_cvt_u32_f32_e32 v201, v201
	v_cvt_u32_f32_e32 v202, v202
	v_cvt_u32_f32_e32 v203, v203
	v_cvt_u32_f32_e32 v204, v204
	v_cvt_u32_f32_e32 v205, v205
	v_lshl_or_b32 v198, v199, 8, v198
	v_lshl_or_b32 v200, v201, 8, v200
	v_lshl_or_b32 v202, v203, 8, v202
	v_lshl_or_b32 v204, v205, 8, v204
	v_lshl_or_b32 v228, v200, 16, v198
	v_lshl_or_b32 v229, v204, 16, v202
	global_store_dwordx2 v187, v[228:229], s[54:55] offset:32
	v_add_u32_e32 v187, 0xa0000, v186
	v_pk_mul_f32 v[190:191], v[32:33], s[38:39]
	v_pk_mul_f32 v[192:193], v[34:35], s[38:39]
	v_pk_mul_f32 v[194:195], v[28:29], s[38:39]
	v_pk_mul_f32 v[196:197], v[30:31], s[38:39]
	v_exp_f32_e32 v190, v190
	v_exp_f32_e32 v191, v191
	v_exp_f32_e32 v192, v192
	v_exp_f32_e32 v193, v193
	v_exp_f32_e32 v194, v194
	v_exp_f32_e32 v195, v195
	v_exp_f32_e32 v196, v196
	v_exp_f32_e32 v197, v197
	v_pk_add_f32 v[190:191], v[190:191], s[42:43]
	v_pk_add_f32 v[192:193], v[192:193], s[42:43]
	v_pk_add_f32 v[194:195], v[194:195], s[42:43]
	v_pk_add_f32 v[196:197], v[196:197], s[42:43]
	v_rcp_f32_e32 v190, v190
	v_rcp_f32_e32 v191, v191
	v_rcp_f32_e32 v192, v192
	v_rcp_f32_e32 v193, v193
	v_rcp_f32_e32 v194, v194
	v_rcp_f32_e32 v195, v195
	v_rcp_f32_e32 v196, v196
	v_rcp_f32_e32 v197, v197
	v_pk_fma_f32 v[190:191], v[190:191], s[40:41], 0.5 op_sel_hi:[1,1,0]
	v_pk_fma_f32 v[192:193], v[192:193], s[40:41], 0.5 op_sel_hi:[1,1,0]
	v_pk_fma_f32 v[194:195], v[194:195], s[40:41], 0.5 op_sel_hi:[1,1,0]
; __device__ __forceinline__ float fast_rcp(float x) { return __builtin_amdgcn_rcpf(x); }
; __device__ __forceinline__ float fast_exp2(float x) { return __builtin_amdgcn_exp2f(x); }
; __device__ __forceinline__ float sigmoid_f(float x) { return fast_rcp(1.0f + fast_exp2(-1.4426950409f * x)); }
; __device__ __forceinline__ float gelu_tanh(float x) { const float t = x + 0.044715f * x * x * x; return x * fast_rcp(1.0f + fast_exp2(-2.3022081981f * t)); }
; __device__ __forceinline__ f32x4 gelu4(f32x4 v) { return (f32x4){gelu_tanh(v[0]), gelu_tanh(v[1]), gelu_tanh(v[2]), gelu_tanh(v[3])}; }
; __device__ __forceinline__ f32x4 sigm4(f32x4 v) { return (f32x4){sigmoid_f(v[0]), sigmoid_f(v[1]), sigmoid_f(v[2]), sigmoid_f(v[3])}; }
;     __device__ __forceinline__ void operator()(f32x4 (&acc)[2][2][4][2], const Unit& u, int wr, int wc, int fr, int fq) const {
;     ...
;                         if (mode == 3) { u32x2 w; w.x = gate_q4(sigm4(v0)); w.y = gate_q4(sigm4(v1)); *(u32x2*)((unsigned char*)Gt + (size_t)row * 4096 + col0 + bj * 32) = w; continue; }
	v_pk_fma_f32 v[196:197], v[196:197], s[40:41], 0.5 op_sel_hi:[1,1,0]
	v_cvt_u32_f32_e32 v190, v190
	v_cvt_u32_f32_e32 v191, v191
	v_cvt_u32_f32_e32 v192, v192
	v_cvt_u32_f32_e32 v193, v193
	v_cvt_u32_f32_e32 v194, v194
	v_cvt_u32_f32_e32 v195, v195
	v_cvt_u32_f32_e32 v196, v196
	v_cvt_u32_f32_e32 v197, v197
	v_lshl_or_b32 v190, v191, 8, v190
	v_lshl_or_b32 v192, v193, 8, v192
	v_lshl_or_b32 v194, v195, 8, v194
	v_lshl_or_b32 v196, v197, 8, v196
	v_lshl_or_b32 v206, v192, 16, v190
	v_lshl_or_b32 v207, v196, 16, v194
	global_store_dwordx2 v187, v[206:207], s[54:55]
	v_pk_mul_f32 v[198:199], v[24:25], s[38:39]
	v_pk_mul_f32 v[200:201], v[26:27], s[38:39]
	v_pk_mul_f32 v[202:203], v[20:21], s[38:39]
	v_pk_mul_f32 v[204:205], v[22:23], s[38:39]
	v_exp_f32_e32 v198, v198
	v_exp_f32_e32 v199, v199
	v_exp_f32_e32 v200, v200
	v_exp_f32_e32 v201, v201
	v_exp_f32_e32 v202, v202
	v_exp_f32_e32 v203, v203
	v_exp_f32_e32 v204, v204
	v_exp_f32_e32 v205, v205
	v_pk_add_f32 v[198:199], v[198:199], s[42:43]
	v_pk_add_f32 v[200:201], v[200:201], s[42:43]
	v_pk_add_f32 v[202:203], v[202:203], s[42:43]
	v_pk_add_f32 v[204:205], v[204:205], s[42:43]
	v_rcp_f32_e32 v198, v198
	v_rcp_f32_e32 v199, v199
	v_rcp_f32_e32 v200, v200
	v_rcp_f32_e32 v201, v201
	v_rcp_f32_e32 v202, v202
	v_rcp_f32_e32 v203, v203
	v_rcp_f32_e32 v204, v204
	v_rcp_f32_e32 v205, v205
	v_pk_fma_f32 v[198:199], v[198:199], s[40:41], 0.5 op_sel_hi:[1,1,0]
	v_pk_fma_f32 v[200:201], v[200:201], s[40:41], 0.5 op_sel_hi:[1,1,0]
	v_pk_fma_f32 v[202:203], v[202:203], s[40:41], 0.5 op_sel_hi:[1,1,0]
	v_pk_fma_f32 v[204:205], v[204:205], s[40:41], 0.5 op_sel_hi:[1,1,0]
	v_cvt_u32_f32_e32 v198, v198
	v_cvt_u32_f32_e32 v199, v199
	v_cvt_u32_f32_e32 v200, v200
	v_cvt_u32_f32_e32 v201, v201
	v_cvt_u32_f32_e32 v202, v202
	v_cvt_u32_f32_e32 v203, v203
	v_cvt_u32_f32_e32 v204, v204
	v_cvt_u32_f32_e32 v205, v205
	v_lshl_or_b32 v198, v199, 8, v198
	v_lshl_or_b32 v200, v201, 8, v200
	v_lshl_or_b32 v202, v203, 8, v202
	v_lshl_or_b32 v204, v205, 8, v204
	v_lshl_or_b32 v218, v200, 16, v198
	v_lshl_or_b32 v219, v204, 16, v202
	global_store_dwordx2 v187, v[218:219], s[54:55] offset:32
	v_add_u32_e32 v187, 0xb0000, v186
	v_pk_mul_f32 v[190:191], v[16:17], s[38:39]
	v_pk_mul_f32 v[192:193], v[18:19], s[38:39]
	v_pk_mul_f32 v[194:195], v[12:13], s[38:39]
	v_pk_mul_f32 v[196:197], v[14:15], s[38:39]
	v_exp_f32_e32 v190, v190
	v_exp_f32_e32 v191, v191
	v_exp_f32_e32 v192, v192
	v_exp_f32_e32 v193, v193
	v_exp_f32_e32 v194, v194
	v_exp_f32_e32 v195, v195
	v_exp_f32_e32 v196, v196
	v_exp_f32_e32 v197, v197
	v_pk_add_f32 v[190:191], v[190:191], s[42:43]
	v_pk_add_f32 v[192:193], v[192:193], s[42:43]
	v_pk_add_f32 v[194:195], v[194:195], s[42:43]
	v_pk_add_f32 v[196:197], v[196:197], s[42:43]
	v_rcp_f32_e32 v190, v190
	v_rcp_f32_e32 v191, v191
	v_rcp_f32_e32 v192, v192
	v_rcp_f32_e32 v193, v193
	v_rcp_f32_e32 v194, v194
	v_rcp_f32_e32 v195, v195
	v_rcp_f32_e32 v196, v196
	v_rcp_f32_e32 v197, v197
	v_pk_fma_f32 v[190:191], v[190:191], s[40:41], 0.5 op_sel_hi:[1,1,0]
	v_pk_fma_f32 v[192:193], v[192:193], s[40:41], 0.5 op_sel_hi:[1,1,0]
	v_pk_fma_f32 v[194:195], v[194:195], s[40:41], 0.5 op_sel_hi:[1,1,0]
	v_pk_fma_f32 v[196:197], v[196:197], s[40:41], 0.5 op_sel_hi:[1,1,0]
	v_cvt_u32_f32_e32 v190, v190
	v_cvt_u32_f32_e32 v191, v191
	v_cvt_u32_f32_e32 v192, v192
	v_cvt_u32_f32_e32 v193, v193
	v_cvt_u32_f32_e32 v194, v194
	v_cvt_u32_f32_e32 v195, v195
	v_cvt_u32_f32_e32 v196, v196
	v_cvt_u32_f32_e32 v197, v197
	v_lshl_or_b32 v190, v191, 8, v190
	v_lshl_or_b32 v192, v193, 8, v192
	v_lshl_or_b32 v194, v195, 8, v194
	v_lshl_or_b32 v196, v197, 8, v196
	v_lshl_or_b32 v224, v192, 16, v190
	v_lshl_or_b32 v225, v196, 16, v194
	global_store_dwordx2 v187, v[224:225], s[54:55]
	v_pk_mul_f32 v[198:199], v[8:9], s[38:39]
	v_pk_mul_f32 v[200:201], v[10:11], s[38:39]
	v_pk_mul_f32 v[202:203], v[4:5], s[38:39]
	v_pk_mul_f32 v[204:205], v[6:7], s[38:39]
	v_exp_f32_e32 v198, v198
	v_exp_f32_e32 v199, v199
	v_exp_f32_e32 v200, v200
	v_exp_f32_e32 v201, v201
	v_exp_f32_e32 v202, v202
	v_exp_f32_e32 v203, v203
	v_exp_f32_e32 v204, v204
	v_exp_f32_e32 v205, v205
	v_pk_add_f32 v[198:199], v[198:199], s[42:43]
	v_pk_add_f32 v[200:201], v[200:201], s[42:43]
	v_pk_add_f32 v[202:203], v[202:203], s[42:43]
	v_pk_add_f32 v[204:205], v[204:205], s[42:43]
	v_rcp_f32_e32 v198, v198
	v_rcp_f32_e32 v199, v199
	v_rcp_f32_e32 v200, v200
	v_rcp_f32_e32 v201, v201
	v_rcp_f32_e32 v202, v202
	v_rcp_f32_e32 v203, v203
	v_rcp_f32_e32 v204, v204
	v_rcp_f32_e32 v205, v205
	v_pk_fma_f32 v[198:199], v[198:199], s[40:41], 0.5 op_sel_hi:[1,1,0]
	v_pk_fma_f32 v[200:201], v[200:201], s[40:41], 0.5 op_sel_hi:[1,1,0]
	v_pk_fma_f32 v[202:203], v[202:203], s[40:41], 0.5 op_sel_hi:[1,1,0]
	v_pk_fma_f32 v[204:205], v[204:205], s[40:41], 0.5 op_sel_hi:[1,1,0]
	v_cvt_u32_f32_e32 v198, v198
	v_cvt_u32_f32_e32 v199, v199
	v_cvt_u32_f32_e32 v200, v200
	v_cvt_u32_f32_e32 v201, v201
	v_cvt_u32_f32_e32 v202, v202
	v_cvt_u32_f32_e32 v203, v203
	v_cvt_u32_f32_e32 v204, v204
	v_cvt_u32_f32_e32 v205, v205
	v_lshl_or_b32 v198, v199, 8, v198
	v_lshl_or_b32 v200, v201, 8, v200
	v_lshl_or_b32 v202, v203, 8, v202
	v_lshl_or_b32 v204, v205, 8, v204
	v_lshl_or_b32 v228, v200, 16, v198
	v_lshl_or_b32 v229, v204, 16, v202
	global_store_dwordx2 v187, v[228:229], s[54:55] offset:32
.Lp1e_done:
	s_branch .LBB0_354
.LBB0_199:
	v_cmp_lt_i32_e32 vcc, 5, v210
	s_and_saveexec_b64 s[12:13], vcc
	s_xor_b64 s[12:13], exec, s[12:13]
	s_cbranch_execz .LBB0_207
	v_cmp_lt_i32_e32 vcc, 6, v210
	s_and_saveexec_b64 s[20:21], vcc
	s_xor_b64 s[42:43], exec, s[20:21]
	s_cbranch_execz .LBB0_204
	v_cmp_eq_u32_e32 vcc, 7, v210
	s_and_saveexec_b64 s[52:53], vcc
	s_cbranch_execz .LBB0_203
	s_mov_b64 s[40:41], exec
	s_waitcnt lgkmcnt(0)
	v_pk_add_f32 v[134:135], v[204:205], v[208:209]

; template <class Epi, class SchedT, bool ALIGN_EPI, bool SP2>
; __device__ __forceinline__ void gemm_phase(LAS unsigned char* lds, const int ldk, const int nt, const SchedT& S, const Epi& E) {
;     ...
;         if constexpr (ALIGN_EPI) { if (wr == 0) PG8_BAR; }
;         E(acc, cur, wr, wc, fr, fq);
;         if (!has_next) break;
;         if (!(SchedT::kMode == 2 && cur.kind == 0)) {
; #pragma unroll
;         for (int a = 0; a < 2; ++a)
; #pragma unroll
;             for (int b = 0; b < 2; ++b)
; #pragma unroll
;                 for (int m = 0; m < 4; ++m)
; #pragma unroll
;                     for (int n = 0; n < 2; ++n) acc[a][b][m][n] = (f32x4){0.f, 0.f, 0.f, 0.f};
;         }
;         cur = nxt; cA = nA; cB = nB; ++ui;
;         if constexpr (ALIGN_EPI) { if (wr == 1) PG8_BAR; }
;     }
;     __device__ __forceinline__ void operator()(f32x4 (&acc)[2][2][4][2], const Unit& u, int wr, int wc, int fr, int fq) const {
;         if (u.kind == 0) {
;             const int pn = u.pn; bf16_t* base; int ldc, colt, mode;
;             if (pn < 4) { base = U; ldc = 1024; colt = pn * 256; mode = 0; }
;             else if (pn < 12) { base = Q; ldc = 1024; colt = (pn - 8) * 256; mode = 1; }
;             else if (pn < 16) { base = Kb; ldc = 1024; colt = (pn - 12) * 256; mode = 2; }
;             else { base = U; ldc = 4096; colt = (pn - 20) * 256; mode = 3; }
;             const int row0 = u.pm * BM + wr * 64 + fr, col0 = colt + wc * 64 + 8 * fq;
; #pragma unroll
;             for (int ai = 0; ai < 2; ++ai)
; #pragma unroll
;                 for (int m = 0; m < 4; ++m) {
;                     const int row = row0 + ai * HALF + m * 16;
;                     float rstd = row_rstd(ss, row, fq); if (mode == 1) rstd *= 0.125f;
;                     bf16_t* rowp = base + (size_t)row * ldc + col0;
; #pragma unroll
;                     for (int bj = 0; bj < 2; ++bj) {
;                         f32x4 v0 = acc[ai][bj][m][0] * rstd, v1 = acc[ai][bj][m][1] * rstd;
;                         if (mode == 3) { u32x2 w; w.x = gate_q4(sigm4(v0)); w.y = gate_q4(sigm4(v1)); *(u32x2*)((unsigned char*)Gt + (size_t)row * 4096 + col0 + bj * 32) = w; continue; }
;                         if (mode == 0) { v0 = gelu4(v0); v1 = gelu4(v1); }
;                         *(u32x4*)(rowp + bj * 32) = pack8(v0, v1);
;                     }
;                 }
.LBB0_245:
.LBB0_246:
.LBB0_247:
.LBB0_249:
.LBB0_252:
.LBB0_253:
.LBB0_254:
.LBB0_256:
.LBB0_259:
.LBB0_260:
.LBB0_261:
.LBB0_263:
.LBB0_266:
.LBB0_267:
.LBB0_268:
.LBB0_270:
.LBB0_273:
.LBB0_274:
.LBB0_275:
.LBB0_277:
.LBB0_280:
.LBB0_281:
.LBB0_282:
.LBB0_284:
.LBB0_287:
.LBB0_288:
.LBB0_289:
.LBB0_291:
.LBB0_294:
.LBB0_295:
.LBB0_296:
.LBB0_298:
.LBB0_301:
.LBB0_302:
.LBB0_303:
.LBB0_305:
.LBB0_308:
.LBB0_309:
.LBB0_310:
.LBB0_312:
.LBB0_315:
.LBB0_316:
.LBB0_317:
.LBB0_319:
.LBB0_322:
.LBB0_323:
.LBB0_324:
.LBB0_326:
.LBB0_329:
.LBB0_330:
.LBB0_331:
.LBB0_333:
.LBB0_336:
.LBB0_337:
.LBB0_338:
.LBB0_340:
.LBB0_343:
.LBB0_344:
.LBB0_345:
.LBB0_347:
.LBB0_350:
.LBB0_351:
.LBB0_352:
.LBB0_354:
	s_and_b64 vcc, exec, s[36:37]
	s_mov_b64 s[0:1], -1
	s_cbranch_vccnz .LBB0_117
	s_andn2_b64 vcc, exec, s[46:47]
	s_cbranch_vccnz .LBB0_116
	s_barrier
	s_branch .LBB0_116
